# inproj0 main loop hand-rewritten: DMA issue spread through MFMA stream, LDS fragment reads software-pipelined, barrier mid-stream
# speedup vs baseline: 1.0250x; 1.0250x over previous
.LBB0_171:
	s_ashr_i32 s1, s75, 31
	s_lshr_b32 s1, s1, 23
	s_add_i32 s1, s75, s1
	s_ashr_i32 s1, s1, 9
	s_and_b32 s0, s75, 7
	s_lshl_b32 s1, s1, 3
	s_or_b32 s34, s1, s0
	s_mul_hi_i32 s0, s34, 0x92492493
	s_add_i32 s0, s0, s34
	s_lshr_b32 s1, s0, 31
	s_ashr_i32 s70, s0, 2
	s_add_i32 s70, s70, s1
	s_lshl_b32 s0, s70, 3
	s_bfe_u32 s1, s75, 0x30003
	s_or_b32 s66, s0, s1
	s_mul_i32 s0, s70, 7
	s_sub_i32 s77, s34, s0
	s_lshl_b32 s0, s77, 3
	s_bfe_u32 s76, s75, 0x30006
	s_or_b32 s0, s0, s76
	s_ashr_i32 s67, s66, 31
	s_ashr_i32 s1, s0, 31
	s_lshl_b64 s[4:5], s[0:1], 18
	s_lshl_b64 s[6:7], s[66:67], 18
	s_barrier
	s_lshl_b64 s[64:65], s[66:67], 17
	s_add_u32 s84, s50, 0x3a00000
	s_addc_u32 s85, s51, 0
	s_add_u32 s84, s84, s6
	s_addc_u32 s85, s85, s7
	s_add_u32 s86, s50, 0x1a00000
	s_addc_u32 s87, s51, 0
	s_add_u32 s86, s86, s4
	s_addc_u32 s87, s87, s5
	v_readfirstlane_b32 s1, v129
	v_and_b32_e32 v80, 15, v131
	v_bfe_u32 v81, v131, 4, 2
	v_bfe_u32 v82, v131, 1, 3
	v_xor_b32_e32 v82, v81, v82
	v_lshlrev_b32_e32 v82, 4, v82
	v_lshl_or_b32 v218, v80, 7, v82
	v_xor_b32_e32 v220, 64, v218
	v_lshrrev_b32_e32 v82, 6, v131
	v_lshl_add_u32 v142, v82, 12, v218
	v_lshl_add_u32 v216, v82, 12, v220
	v_bfe_u32 v80, v131, 4, 3
	v_and_b32_e32 v81, 7, v131
	v_xor_b32_e32 v80, v80, v81
	v_lshlrev_b32_e32 v80, 4, v80
	v_lshrrev_b32_e32 v81, 3, v131
	v_lshl_or_b32 v222, v81, 11, v80
	v_add_u32_e32 v224, 65536, v222
	v_add_u32_e32 v226, 131072, v222
	v_add_u32_e32 v228, 196608, v222
	s_add_u32 m0, s1, 0
	v_mov_b32_e32 v0, 0
	v_mov_b32_e32 v1, 0
	global_load_lds_dwordx4 v222, s[84:85]
	s_add_u32 m0, s1, 4096
	v_mov_b32_e32 v2, 0
	v_mov_b32_e32 v3, 0
	global_load_lds_dwordx4 v224, s[84:85]
	s_add_u32 m0, s1, 8192
	v_mov_b32_e32 v4, 0
	v_mov_b32_e32 v5, 0
	global_load_lds_dwordx4 v226, s[84:85]
	s_add_u32 m0, s1, 12288
	v_mov_b32_e32 v6, 0
	v_mov_b32_e32 v7, 0
	global_load_lds_dwordx4 v228, s[84:85]
	s_add_u32 s84, s84, 128
	s_addc_u32 s85, s85, 0
	s_add_u32 m0, s1, 16384
	v_mov_b32_e32 v8, 0
	v_mov_b32_e32 v9, 0
	global_load_lds_dwordx4 v222, s[86:87]
	s_add_u32 m0, s1, 20480
	v_mov_b32_e32 v10, 0
	v_mov_b32_e32 v11, 0
	global_load_lds_dwordx4 v224, s[86:87]
	s_add_u32 m0, s1, 24576
	v_mov_b32_e32 v12, 0
	v_mov_b32_e32 v13, 0
	global_load_lds_dwordx4 v226, s[86:87]
	s_add_u32 m0, s1, 28672
	v_mov_b32_e32 v14, 0
	v_mov_b32_e32 v15, 0
	global_load_lds_dwordx4 v228, s[86:87]
	s_add_u32 s86, s86, 128
	s_addc_u32 s87, s87, 0
	s_add_u32 m0, s1, 32768
	v_mov_b32_e32 v16, 0
	v_mov_b32_e32 v17, 0
	global_load_lds_dwordx4 v222, s[84:85]
	s_add_u32 m0, s1, 36864
	v_mov_b32_e32 v18, 0
	v_mov_b32_e32 v19, 0
	global_load_lds_dwordx4 v224, s[84:85]
	s_add_u32 m0, s1, 40960
	v_mov_b32_e32 v20, 0
	v_mov_b32_e32 v21, 0
	global_load_lds_dwordx4 v226, s[84:85]
	s_add_u32 m0, s1, 45056
	v_mov_b32_e32 v22, 0
	v_mov_b32_e32 v23, 0
	global_load_lds_dwordx4 v228, s[84:85]
	s_add_u32 s84, s84, 128
	s_addc_u32 s85, s85, 0
	s_add_u32 m0, s1, 49152
	v_mov_b32_e32 v24, 0
	v_mov_b32_e32 v25, 0
	global_load_lds_dwordx4 v222, s[86:87]
	s_add_u32 m0, s1, 53248
	v_mov_b32_e32 v26, 0
	v_mov_b32_e32 v27, 0
	global_load_lds_dwordx4 v224, s[86:87]
	s_add_u32 m0, s1, 57344
	v_mov_b32_e32 v28, 0
	v_mov_b32_e32 v29, 0
	global_load_lds_dwordx4 v226, s[86:87]
	s_add_u32 m0, s1, 61440
	v_mov_b32_e32 v30, 0
	v_mov_b32_e32 v31, 0
	global_load_lds_dwordx4 v228, s[86:87]
	s_add_u32 s86, s86, 128
	s_addc_u32 s87, s87, 0
	v_mov_b32_e32 v32, 0
	v_mov_b32_e32 v33, 0
	v_mov_b32_e32 v34, 0
	v_mov_b32_e32 v35, 0
	v_mov_b32_e32 v36, 0
	v_mov_b32_e32 v37, 0
	v_mov_b32_e32 v38, 0
	v_mov_b32_e32 v39, 0
	v_mov_b32_e32 v40, 0
	v_mov_b32_e32 v41, 0
	v_mov_b32_e32 v42, 0
	v_mov_b32_e32 v43, 0
	v_mov_b32_e32 v44, 0
	v_mov_b32_e32 v45, 0
	v_mov_b32_e32 v46, 0
	v_mov_b32_e32 v47, 0
	v_mov_b32_e32 v48, 0
	v_mov_b32_e32 v49, 0
	v_mov_b32_e32 v50, 0
	v_mov_b32_e32 v51, 0
	v_mov_b32_e32 v52, 0
	v_mov_b32_e32 v53, 0
	v_mov_b32_e32 v54, 0
	v_mov_b32_e32 v55, 0
	v_mov_b32_e32 v56, 0
	v_mov_b32_e32 v57, 0
	v_mov_b32_e32 v58, 0
	v_mov_b32_e32 v59, 0
	v_mov_b32_e32 v60, 0
	v_mov_b32_e32 v61, 0
	v_mov_b32_e32 v62, 0
	v_mov_b32_e32 v63, 0
	s_waitcnt vmcnt(8)
	s_barrier
	ds_read_b128 v[64:67], v142 offset:0
	ds_read_b128 v[68:71], v142 offset:2048
	ds_read_b128 v[80:83], v218 offset:16384
	ds_read_b128 v[84:87], v218 offset:18432
	ds_read_b128 v[88:91], v218 offset:20480
	ds_read_b128 v[92:95], v218 offset:22528
	ds_read_b128 v[96:99], v218 offset:24576
	ds_read_b128 v[100:103], v218 offset:26624
	ds_read_b128 v[104:107], v218 offset:28672
	s_waitcnt lgkmcnt(6)
	v_mfma_f32_16x16x32_bf16 v[0:3], v[64:67], v[80:83], v[0:3]
	v_mfma_f32_16x16x32_bf16 v[32:35], v[68:71], v[80:83], v[32:35]
	ds_read_b128 v[108:111], v218 offset:30720
	s_waitcnt lgkmcnt(6)
	v_mfma_f32_16x16x32_bf16 v[4:7], v[64:67], v[84:87], v[4:7]
	v_mfma_f32_16x16x32_bf16 v[36:39], v[68:71], v[84:87], v[36:39]
	ds_read_b128 v[72:75], v216 offset:0
	ds_read_b128 v[76:79], v216 offset:2048
	ds_read_b128 v[112:115], v220 offset:16384
	s_waitcnt lgkmcnt(8)
	v_mfma_f32_16x16x32_bf16 v[8:11], v[64:67], v[88:91], v[8:11]
	v_mfma_f32_16x16x32_bf16 v[40:43], v[68:71], v[88:91], v[40:43]
	ds_read_b128 v[116:119], v220 offset:18432
	s_waitcnt lgkmcnt(8)
	v_mfma_f32_16x16x32_bf16 v[12:15], v[64:67], v[92:95], v[12:15]
	v_mfma_f32_16x16x32_bf16 v[44:47], v[68:71], v[92:95], v[44:47]
	ds_read_b128 v[120:123], v220 offset:20480
	s_waitcnt lgkmcnt(8)
	v_mfma_f32_16x16x32_bf16 v[16:19], v[64:67], v[96:99], v[16:19]
	v_mfma_f32_16x16x32_bf16 v[48:51], v[68:71], v[96:99], v[48:51]
	ds_read_b128 v[124:127], v220 offset:22528
	s_waitcnt lgkmcnt(8)
	v_mfma_f32_16x16x32_bf16 v[20:23], v[64:67], v[100:103], v[20:23]
	v_mfma_f32_16x16x32_bf16 v[52:55], v[68:71], v[100:103], v[52:55]
	ds_read_b128 v[80:83], v220 offset:24576
	s_waitcnt lgkmcnt(8)
	v_mfma_f32_16x16x32_bf16 v[24:27], v[64:67], v[104:107], v[24:27]
	v_mfma_f32_16x16x32_bf16 v[56:59], v[68:71], v[104:107], v[56:59]
	ds_read_b128 v[84:87], v220 offset:26624
	s_waitcnt lgkmcnt(8)
	v_mfma_f32_16x16x32_bf16 v[28:31], v[64:67], v[108:111], v[28:31]
	v_mfma_f32_16x16x32_bf16 v[60:63], v[68:71], v[108:111], v[60:63]
	ds_read_b128 v[88:91], v220 offset:28672
	s_waitcnt lgkmcnt(6)
	v_mfma_f32_16x16x32_bf16 v[0:3], v[72:75], v[112:115], v[0:3]
	v_mfma_f32_16x16x32_bf16 v[32:35], v[76:79], v[112:115], v[32:35]
	ds_read_b128 v[92:95], v220 offset:30720
	s_waitcnt vmcnt(0) lgkmcnt(0)
	s_barrier
	s_add_u32 m0, s1, 0
	s_nop 0
	global_load_lds_dwordx4 v222, s[84:85]
	s_waitcnt lgkmcnt(6)
	v_mfma_f32_16x16x32_bf16 v[4:7], v[72:75], v[116:119], v[4:7]
	v_mfma_f32_16x16x32_bf16 v[36:39], v[76:79], v[116:119], v[36:39]
	ds_read_b128 v[64:67], v142 offset:32768
	ds_read_b128 v[68:71], v142 offset:34816
	ds_read_b128 v[96:99], v218 offset:49152
	s_add_u32 m0, s1, 4096
	s_nop 0
	global_load_lds_dwordx4 v224, s[84:85]
	s_waitcnt lgkmcnt(8)
	v_mfma_f32_16x16x32_bf16 v[8:11], v[72:75], v[120:123], v[8:11]
	v_mfma_f32_16x16x32_bf16 v[40:43], v[76:79], v[120:123], v[40:43]
	ds_read_b128 v[100:103], v218 offset:51200
	s_add_u32 m0, s1, 8192
	s_nop 0
	global_load_lds_dwordx4 v226, s[84:85]
	s_waitcnt lgkmcnt(8)
	v_mfma_f32_16x16x32_bf16 v[12:15], v[72:75], v[124:127], v[12:15]
	v_mfma_f32_16x16x32_bf16 v[44:47], v[76:79], v[124:127], v[44:47]
	ds_read_b128 v[104:107], v218 offset:53248
	s_add_u32 m0, s1, 12288
	s_nop 0
	global_load_lds_dwordx4 v228, s[84:85]
	s_add_u32 s84, s84, 128
	s_addc_u32 s85, s85, 0
	s_waitcnt lgkmcnt(8)
	v_mfma_f32_16x16x32_bf16 v[16:19], v[72:75], v[80:83], v[16:19]
	v_mfma_f32_16x16x32_bf16 v[48:51], v[76:79], v[80:83], v[48:51]
	ds_read_b128 v[108:111], v218 offset:55296
	s_add_u32 m0, s1, 16384
	s_nop 0
	global_load_lds_dwordx4 v222, s[86:87]
	s_waitcnt lgkmcnt(8)
	v_mfma_f32_16x16x32_bf16 v[20:23], v[72:75], v[84:87], v[20:23]
	v_mfma_f32_16x16x32_bf16 v[52:55], v[76:79], v[84:87], v[52:55]
	ds_read_b128 v[112:115], v218 offset:57344
	s_add_u32 m0, s1, 20480
	s_nop 0
	global_load_lds_dwordx4 v224, s[86:87]
	s_waitcnt lgkmcnt(8)
	v_mfma_f32_16x16x32_bf16 v[24:27], v[72:75], v[88:91], v[24:27]
	v_mfma_f32_16x16x32_bf16 v[56:59], v[76:79], v[88:91], v[56:59]
	ds_read_b128 v[116:119], v218 offset:59392
	s_add_u32 m0, s1, 24576
	s_nop 0
	global_load_lds_dwordx4 v226, s[86:87]
	s_waitcnt lgkmcnt(8)
	v_mfma_f32_16x16x32_bf16 v[28:31], v[72:75], v[92:95], v[28:31]
	v_mfma_f32_16x16x32_bf16 v[60:63], v[76:79], v[92:95], v[60:63]
	ds_read_b128 v[120:123], v218 offset:61440
	s_add_u32 m0, s1, 28672
	s_nop 0
	global_load_lds_dwordx4 v228, s[86:87]
	s_add_u32 s86, s86, 128
	s_addc_u32 s87, s87, 0
	s_waitcnt lgkmcnt(6)
	v_mfma_f32_16x16x32_bf16 v[0:3], v[64:67], v[96:99], v[0:3]
	v_mfma_f32_16x16x32_bf16 v[32:35], v[68:71], v[96:99], v[32:35]
	ds_read_b128 v[124:127], v218 offset:63488
	s_waitcnt lgkmcnt(6)
	v_mfma_f32_16x16x32_bf16 v[4:7], v[64:67], v[100:103], v[4:7]
	v_mfma_f32_16x16x32_bf16 v[36:39], v[68:71], v[100:103], v[36:39]
	ds_read_b128 v[72:75], v216 offset:32768
	ds_read_b128 v[76:79], v216 offset:34816
	ds_read_b128 v[80:83], v220 offset:49152
	s_waitcnt lgkmcnt(8)
	v_mfma_f32_16x16x32_bf16 v[8:11], v[64:67], v[104:107], v[8:11]
	v_mfma_f32_16x16x32_bf16 v[40:43], v[68:71], v[104:107], v[40:43]
	ds_read_b128 v[84:87], v220 offset:51200
	s_waitcnt lgkmcnt(8)
	v_mfma_f32_16x16x32_bf16 v[12:15], v[64:67], v[108:111], v[12:15]
	v_mfma_f32_16x16x32_bf16 v[44:47], v[68:71], v[108:111], v[44:47]
	ds_read_b128 v[88:91], v220 offset:53248
	s_waitcnt lgkmcnt(8)
	v_mfma_f32_16x16x32_bf16 v[16:19], v[64:67], v[112:115], v[16:19]
	v_mfma_f32_16x16x32_bf16 v[48:51], v[68:71], v[112:115], v[48:51]
	ds_read_b128 v[92:95], v220 offset:55296
	s_waitcnt lgkmcnt(8)
	v_mfma_f32_16x16x32_bf16 v[20:23], v[64:67], v[116:119], v[20:23]
	v_mfma_f32_16x16x32_bf16 v[52:55], v[68:71], v[116:119], v[52:55]
	ds_read_b128 v[96:99], v220 offset:57344
	s_waitcnt lgkmcnt(8)
	v_mfma_f32_16x16x32_bf16 v[24:27], v[64:67], v[120:123], v[24:27]
	v_mfma_f32_16x16x32_bf16 v[56:59], v[68:71], v[120:123], v[56:59]
	ds_read_b128 v[100:103], v220 offset:59392
	s_waitcnt lgkmcnt(8)
	v_mfma_f32_16x16x32_bf16 v[28:31], v[64:67], v[124:127], v[28:31]
	v_mfma_f32_16x16x32_bf16 v[60:63], v[68:71], v[124:127], v[60:63]
	ds_read_b128 v[104:107], v220 offset:61440
	s_waitcnt lgkmcnt(6)
	v_mfma_f32_16x16x32_bf16 v[0:3], v[72:75], v[80:83], v[0:3]
	v_mfma_f32_16x16x32_bf16 v[32:35], v[76:79], v[80:83], v[32:35]
	ds_read_b128 v[108:111], v220 offset:63488
	s_waitcnt vmcnt(0) lgkmcnt(0)
	s_barrier
	s_add_u32 m0, s1, 32768
	s_nop 0
	global_load_lds_dwordx4 v222, s[84:85]
	s_waitcnt lgkmcnt(6)
	v_mfma_f32_16x16x32_bf16 v[4:7], v[72:75], v[84:87], v[4:7]
	v_mfma_f32_16x16x32_bf16 v[36:39], v[76:79], v[84:87], v[36:39]
	ds_read_b128 v[64:67], v142 offset:0
	ds_read_b128 v[68:71], v142 offset:2048
	ds_read_b128 v[112:115], v218 offset:16384
	s_add_u32 m0, s1, 36864
	s_nop 0
	global_load_lds_dwordx4 v224, s[84:85]
	s_waitcnt lgkmcnt(8)
	v_mfma_f32_16x16x32_bf16 v[8:11], v[72:75], v[88:91], v[8:11]
	v_mfma_f32_16x16x32_bf16 v[40:43], v[76:79], v[88:91], v[40:43]
	ds_read_b128 v[116:119], v218 offset:18432
	s_add_u32 m0, s1, 40960
	s_nop 0
	global_load_lds_dwordx4 v226, s[84:85]
	s_waitcnt lgkmcnt(8)
	v_mfma_f32_16x16x32_bf16 v[12:15], v[72:75], v[92:95], v[12:15]
	v_mfma_f32_16x16x32_bf16 v[44:47], v[76:79], v[92:95], v[44:47]
	ds_read_b128 v[120:123], v218 offset:20480
	s_add_u32 m0, s1, 45056
	s_nop 0
	global_load_lds_dwordx4 v228, s[84:85]
	s_add_u32 s84, s84, 128
	s_addc_u32 s85, s85, 0
	s_waitcnt lgkmcnt(8)
	v_mfma_f32_16x16x32_bf16 v[16:19], v[72:75], v[96:99], v[16:19]
	v_mfma_f32_16x16x32_bf16 v[48:51], v[76:79], v[96:99], v[48:51]
	ds_read_b128 v[124:127], v218 offset:22528
	s_add_u32 m0, s1, 49152
	s_nop 0
	global_load_lds_dwordx4 v222, s[86:87]
	s_waitcnt lgkmcnt(8)
	v_mfma_f32_16x16x32_bf16 v[20:23], v[72:75], v[100:103], v[20:23]
	v_mfma_f32_16x16x32_bf16 v[52:55], v[76:79], v[100:103], v[52:55]
	ds_read_b128 v[80:83], v218 offset:24576
	s_add_u32 m0, s1, 53248
	s_nop 0
	global_load_lds_dwordx4 v224, s[86:87]
	s_waitcnt lgkmcnt(8)
	v_mfma_f32_16x16x32_bf16 v[24:27], v[72:75], v[104:107], v[24:27]
	v_mfma_f32_16x16x32_bf16 v[56:59], v[76:79], v[104:107], v[56:59]
	ds_read_b128 v[84:87], v218 offset:26624
	s_add_u32 m0, s1, 57344
	s_nop 0
	global_load_lds_dwordx4 v226, s[86:87]
	s_waitcnt lgkmcnt(8)
	v_mfma_f32_16x16x32_bf16 v[28:31], v[72:75], v[108:111], v[28:31]
	v_mfma_f32_16x16x32_bf16 v[60:63], v[76:79], v[108:111], v[60:63]
	ds_read_b128 v[88:91], v218 offset:28672
	s_add_u32 m0, s1, 61440
	s_nop 0
	global_load_lds_dwordx4 v228, s[86:87]
	s_add_u32 s86, s86, 128
	s_addc_u32 s87, s87, 0
	s_waitcnt lgkmcnt(6)
	v_mfma_f32_16x16x32_bf16 v[0:3], v[64:67], v[112:115], v[0:3]
	v_mfma_f32_16x16x32_bf16 v[32:35], v[68:71], v[112:115], v[32:35]
	ds_read_b128 v[92:95], v218 offset:30720
	s_waitcnt lgkmcnt(6)
	v_mfma_f32_16x16x32_bf16 v[4:7], v[64:67], v[116:119], v[4:7]
	v_mfma_f32_16x16x32_bf16 v[36:39], v[68:71], v[116:119], v[36:39]
	ds_read_b128 v[72:75], v216 offset:0
	ds_read_b128 v[76:79], v216 offset:2048
	ds_read_b128 v[96:99], v220 offset:16384
	s_waitcnt lgkmcnt(8)
	v_mfma_f32_16x16x32_bf16 v[8:11], v[64:67], v[120:123], v[8:11]
	v_mfma_f32_16x16x32_bf16 v[40:43], v[68:71], v[120:123], v[40:43]
	ds_read_b128 v[100:103], v220 offset:18432
	s_waitcnt lgkmcnt(8)
	v_mfma_f32_16x16x32_bf16 v[12:15], v[64:67], v[124:127], v[12:15]
	v_mfma_f32_16x16x32_bf16 v[44:47], v[68:71], v[124:127], v[44:47]
	ds_read_b128 v[104:107], v220 offset:20480
	s_waitcnt lgkmcnt(8)
	v_mfma_f32_16x16x32_bf16 v[16:19], v[64:67], v[80:83], v[16:19]
	v_mfma_f32_16x16x32_bf16 v[48:51], v[68:71], v[80:83], v[48:51]
	ds_read_b128 v[108:111], v220 offset:22528
	s_waitcnt lgkmcnt(8)
	v_mfma_f32_16x16x32_bf16 v[20:23], v[64:67], v[84:87], v[20:23]
	v_mfma_f32_16x16x32_bf16 v[52:55], v[68:71], v[84:87], v[52:55]
	ds_read_b128 v[112:115], v220 offset:24576
	s_waitcnt lgkmcnt(8)
	v_mfma_f32_16x16x32_bf16 v[24:27], v[64:67], v[88:91], v[24:27]
	v_mfma_f32_16x16x32_bf16 v[56:59], v[68:71], v[88:91], v[56:59]
	ds_read_b128 v[116:119], v220 offset:26624
	s_waitcnt lgkmcnt(8)
	v_mfma_f32_16x16x32_bf16 v[28:31], v[64:67], v[92:95], v[28:31]
	v_mfma_f32_16x16x32_bf16 v[60:63], v[68:71], v[92:95], v[60:63]
	ds_read_b128 v[120:123], v220 offset:28672
	s_waitcnt lgkmcnt(6)
	v_mfma_f32_16x16x32_bf16 v[0:3], v[72:75], v[96:99], v[0:3]
	v_mfma_f32_16x16x32_bf16 v[32:35], v[76:79], v[96:99], v[32:35]
	ds_read_b128 v[124:127], v220 offset:30720
	s_waitcnt vmcnt(0) lgkmcnt(0)
	s_barrier
	s_add_u32 m0, s1, 0
	s_nop 0
	global_load_lds_dwordx4 v222, s[84:85]
	s_waitcnt lgkmcnt(6)
	v_mfma_f32_16x16x32_bf16 v[4:7], v[72:75], v[100:103], v[4:7]
	v_mfma_f32_16x16x32_bf16 v[36:39], v[76:79], v[100:103], v[36:39]
	ds_read_b128 v[64:67], v142 offset:32768
	ds_read_b128 v[68:71], v142 offset:34816
	ds_read_b128 v[80:83], v218 offset:49152
	s_add_u32 m0, s1, 4096
	s_nop 0
	global_load_lds_dwordx4 v224, s[84:85]
	s_waitcnt lgkmcnt(8)
	v_mfma_f32_16x16x32_bf16 v[8:11], v[72:75], v[104:107], v[8:11]
	v_mfma_f32_16x16x32_bf16 v[40:43], v[76:79], v[104:107], v[40:43]
	ds_read_b128 v[84:87], v218 offset:51200
	s_add_u32 m0, s1, 8192
	s_nop 0
	global_load_lds_dwordx4 v226, s[84:85]
	s_waitcnt lgkmcnt(8)
	v_mfma_f32_16x16x32_bf16 v[12:15], v[72:75], v[108:111], v[12:15]
	v_mfma_f32_16x16x32_bf16 v[44:47], v[76:79], v[108:111], v[44:47]
	ds_read_b128 v[88:91], v218 offset:53248
	s_add_u32 m0, s1, 12288
	s_nop 0
	global_load_lds_dwordx4 v228, s[84:85]
	s_add_u32 s84, s84, 128
	s_addc_u32 s85, s85, 0
	s_waitcnt lgkmcnt(8)
	v_mfma_f32_16x16x32_bf16 v[16:19], v[72:75], v[112:115], v[16:19]
	v_mfma_f32_16x16x32_bf16 v[48:51], v[76:79], v[112:115], v[48:51]
	ds_read_b128 v[92:95], v218 offset:55296
	s_add_u32 m0, s1, 16384
	s_nop 0
	global_load_lds_dwordx4 v222, s[86:87]
	s_waitcnt lgkmcnt(8)
	v_mfma_f32_16x16x32_bf16 v[20:23], v[72:75], v[116:119], v[20:23]
	v_mfma_f32_16x16x32_bf16 v[52:55], v[76:79], v[116:119], v[52:55]
	ds_read_b128 v[96:99], v218 offset:57344
	s_add_u32 m0, s1, 20480
	s_nop 0
	global_load_lds_dwordx4 v224, s[86:87]
	s_waitcnt lgkmcnt(8)
	v_mfma_f32_16x16x32_bf16 v[24:27], v[72:75], v[120:123], v[24:27]
	v_mfma_f32_16x16x32_bf16 v[56:59], v[76:79], v[120:123], v[56:59]
	ds_read_b128 v[100:103], v218 offset:59392
	s_add_u32 m0, s1, 24576
	s_nop 0
	global_load_lds_dwordx4 v226, s[86:87]
	s_waitcnt lgkmcnt(8)
	v_mfma_f32_16x16x32_bf16 v[28:31], v[72:75], v[124:127], v[28:31]
	v_mfma_f32_16x16x32_bf16 v[60:63], v[76:79], v[124:127], v[60:63]
	ds_read_b128 v[104:107], v218 offset:61440
	s_add_u32 m0, s1, 28672
	s_nop 0
	global_load_lds_dwordx4 v228, s[86:87]
	s_add_u32 s86, s86, 128
	s_addc_u32 s87, s87, 0
	s_waitcnt lgkmcnt(6)
	v_mfma_f32_16x16x32_bf16 v[0:3], v[64:67], v[80:83], v[0:3]
	v_mfma_f32_16x16x32_bf16 v[32:35], v[68:71], v[80:83], v[32:35]
	ds_read_b128 v[108:111], v218 offset:63488
	s_waitcnt lgkmcnt(6)
	v_mfma_f32_16x16x32_bf16 v[4:7], v[64:67], v[84:87], v[4:7]
	v_mfma_f32_16x16x32_bf16 v[36:39], v[68:71], v[84:87], v[36:39]
	ds_read_b128 v[72:75], v216 offset:32768
	ds_read_b128 v[76:79], v216 offset:34816
	ds_read_b128 v[112:115], v220 offset:49152
	s_waitcnt lgkmcnt(8)
	v_mfma_f32_16x16x32_bf16 v[8:11], v[64:67], v[88:91], v[8:11]
	v_mfma_f32_16x16x32_bf16 v[40:43], v[68:71], v[88:91], v[40:43]
	ds_read_b128 v[116:119], v220 offset:51200
	s_waitcnt lgkmcnt(8)
	v_mfma_f32_16x16x32_bf16 v[12:15], v[64:67], v[92:95], v[12:15]
	v_mfma_f32_16x16x32_bf16 v[44:47], v[68:71], v[92:95], v[44:47]
	ds_read_b128 v[120:123], v220 offset:53248
	s_waitcnt lgkmcnt(8)
	v_mfma_f32_16x16x32_bf16 v[16:19], v[64:67], v[96:99], v[16:19]
	v_mfma_f32_16x16x32_bf16 v[48:51], v[68:71], v[96:99], v[48:51]
	ds_read_b128 v[124:127], v220 offset:55296
	s_waitcnt lgkmcnt(8)
	v_mfma_f32_16x16x32_bf16 v[20:23], v[64:67], v[100:103], v[20:23]
	v_mfma_f32_16x16x32_bf16 v[52:55], v[68:71], v[100:103], v[52:55]
	ds_read_b128 v[80:83], v220 offset:57344
	s_waitcnt lgkmcnt(8)
	v_mfma_f32_16x16x32_bf16 v[24:27], v[64:67], v[104:107], v[24:27]
	v_mfma_f32_16x16x32_bf16 v[56:59], v[68:71], v[104:107], v[56:59]
	ds_read_b128 v[84:87], v220 offset:59392
	s_waitcnt lgkmcnt(8)
	v_mfma_f32_16x16x32_bf16 v[28:31], v[64:67], v[108:111], v[28:31]
	v_mfma_f32_16x16x32_bf16 v[60:63], v[68:71], v[108:111], v[60:63]
	ds_read_b128 v[88:91], v220 offset:61440
	s_waitcnt lgkmcnt(6)
	v_mfma_f32_16x16x32_bf16 v[0:3], v[72:75], v[112:115], v[0:3]
	v_mfma_f32_16x16x32_bf16 v[32:35], v[76:79], v[112:115], v[32:35]
	ds_read_b128 v[92:95], v220 offset:63488
	s_waitcnt vmcnt(0) lgkmcnt(0)
	s_barrier
	s_add_u32 m0, s1, 32768
	s_nop 0
	global_load_lds_dwordx4 v222, s[84:85]
	s_waitcnt lgkmcnt(6)
	v_mfma_f32_16x16x32_bf16 v[4:7], v[72:75], v[116:119], v[4:7]
	v_mfma_f32_16x16x32_bf16 v[36:39], v[76:79], v[116:119], v[36:39]
	ds_read_b128 v[64:67], v142 offset:0
	ds_read_b128 v[68:71], v142 offset:2048
	ds_read_b128 v[96:99], v218 offset:16384
	s_add_u32 m0, s1, 36864
	s_nop 0
	global_load_lds_dwordx4 v224, s[84:85]
	s_waitcnt lgkmcnt(8)
	v_mfma_f32_16x16x32_bf16 v[8:11], v[72:75], v[120:123], v[8:11]
	v_mfma_f32_16x16x32_bf16 v[40:43], v[76:79], v[120:123], v[40:43]
	ds_read_b128 v[100:103], v218 offset:18432
	s_add_u32 m0, s1, 40960
	s_nop 0
	global_load_lds_dwordx4 v226, s[84:85]
	s_waitcnt lgkmcnt(8)
	v_mfma_f32_16x16x32_bf16 v[12:15], v[72:75], v[124:127], v[12:15]
	v_mfma_f32_16x16x32_bf16 v[44:47], v[76:79], v[124:127], v[44:47]
	ds_read_b128 v[104:107], v218 offset:20480
	s_add_u32 m0, s1, 45056
	s_nop 0
	global_load_lds_dwordx4 v228, s[84:85]
	s_add_u32 s84, s84, 128
	s_addc_u32 s85, s85, 0
	s_waitcnt lgkmcnt(8)
	v_mfma_f32_16x16x32_bf16 v[16:19], v[72:75], v[80:83], v[16:19]
	v_mfma_f32_16x16x32_bf16 v[48:51], v[76:79], v[80:83], v[48:51]
	ds_read_b128 v[108:111], v218 offset:22528
	s_add_u32 m0, s1, 49152
	s_nop 0
	global_load_lds_dwordx4 v222, s[86:87]
	s_waitcnt lgkmcnt(8)
	v_mfma_f32_16x16x32_bf16 v[20:23], v[72:75], v[84:87], v[20:23]
	v_mfma_f32_16x16x32_bf16 v[52:55], v[76:79], v[84:87], v[52:55]
	ds_read_b128 v[112:115], v218 offset:24576
	s_add_u32 m0, s1, 53248
	s_nop 0
	global_load_lds_dwordx4 v224, s[86:87]
	s_waitcnt lgkmcnt(8)
	v_mfma_f32_16x16x32_bf16 v[24:27], v[72:75], v[88:91], v[24:27]
	v_mfma_f32_16x16x32_bf16 v[56:59], v[76:79], v[88:91], v[56:59]
	ds_read_b128 v[116:119], v218 offset:26624
	s_add_u32 m0, s1, 57344
	s_nop 0
	global_load_lds_dwordx4 v226, s[86:87]
	s_waitcnt lgkmcnt(8)
	v_mfma_f32_16x16x32_bf16 v[28:31], v[72:75], v[92:95], v[28:31]
	v_mfma_f32_16x16x32_bf16 v[60:63], v[76:79], v[92:95], v[60:63]
	ds_read_b128 v[120:123], v218 offset:28672
	s_add_u32 m0, s1, 61440
	s_nop 0
	global_load_lds_dwordx4 v228, s[86:87]
	s_add_u32 s86, s86, 128
	s_addc_u32 s87, s87, 0
	s_waitcnt lgkmcnt(6)
	v_mfma_f32_16x16x32_bf16 v[0:3], v[64:67], v[96:99], v[0:3]
	v_mfma_f32_16x16x32_bf16 v[32:35], v[68:71], v[96:99], v[32:35]
	ds_read_b128 v[124:127], v218 offset:30720
	s_waitcnt lgkmcnt(6)
	v_mfma_f32_16x16x32_bf16 v[4:7], v[64:67], v[100:103], v[4:7]
	v_mfma_f32_16x16x32_bf16 v[36:39], v[68:71], v[100:103], v[36:39]
	ds_read_b128 v[72:75], v216 offset:0
	ds_read_b128 v[76:79], v216 offset:2048
	ds_read_b128 v[80:83], v220 offset:16384
	s_waitcnt lgkmcnt(8)
	v_mfma_f32_16x16x32_bf16 v[8:11], v[64:67], v[104:107], v[8:11]
	v_mfma_f32_16x16x32_bf16 v[40:43], v[68:71], v[104:107], v[40:43]
	ds_read_b128 v[84:87], v220 offset:18432
	s_waitcnt lgkmcnt(8)
	v_mfma_f32_16x16x32_bf16 v[12:15], v[64:67], v[108:111], v[12:15]
	v_mfma_f32_16x16x32_bf16 v[44:47], v[68:71], v[108:111], v[44:47]
	ds_read_b128 v[88:91], v220 offset:20480
	s_waitcnt lgkmcnt(8)
	v_mfma_f32_16x16x32_bf16 v[16:19], v[64:67], v[112:115], v[16:19]
	v_mfma_f32_16x16x32_bf16 v[48:51], v[68:71], v[112:115], v[48:51]
	ds_read_b128 v[92:95], v220 offset:22528
	s_waitcnt lgkmcnt(8)
	v_mfma_f32_16x16x32_bf16 v[20:23], v[64:67], v[116:119], v[20:23]
	v_mfma_f32_16x16x32_bf16 v[52:55], v[68:71], v[116:119], v[52:55]
	ds_read_b128 v[96:99], v220 offset:24576
	s_waitcnt lgkmcnt(8)
	v_mfma_f32_16x16x32_bf16 v[24:27], v[64:67], v[120:123], v[24:27]
	v_mfma_f32_16x16x32_bf16 v[56:59], v[68:71], v[120:123], v[56:59]
	ds_read_b128 v[100:103], v220 offset:26624
	s_waitcnt lgkmcnt(8)
	v_mfma_f32_16x16x32_bf16 v[28:31], v[64:67], v[124:127], v[28:31]
	v_mfma_f32_16x16x32_bf16 v[60:63], v[68:71], v[124:127], v[60:63]
	ds_read_b128 v[104:107], v220 offset:28672
	s_waitcnt lgkmcnt(6)
	v_mfma_f32_16x16x32_bf16 v[0:3], v[72:75], v[80:83], v[0:3]
	v_mfma_f32_16x16x32_bf16 v[32:35], v[76:79], v[80:83], v[32:35]
	ds_read_b128 v[108:111], v220 offset:30720
	s_waitcnt vmcnt(0) lgkmcnt(0)
	s_barrier
	s_add_u32 m0, s1, 0
	s_nop 0
	global_load_lds_dwordx4 v222, s[84:85]
	s_waitcnt lgkmcnt(6)
	v_mfma_f32_16x16x32_bf16 v[4:7], v[72:75], v[84:87], v[4:7]
	v_mfma_f32_16x16x32_bf16 v[36:39], v[76:79], v[84:87], v[36:39]
	ds_read_b128 v[64:67], v142 offset:32768
	ds_read_b128 v[68:71], v142 offset:34816
	ds_read_b128 v[112:115], v218 offset:49152
	s_add_u32 m0, s1, 4096
	s_nop 0
	global_load_lds_dwordx4 v224, s[84:85]
	s_waitcnt lgkmcnt(8)
	v_mfma_f32_16x16x32_bf16 v[8:11], v[72:75], v[88:91], v[8:11]
	v_mfma_f32_16x16x32_bf16 v[40:43], v[76:79], v[88:91], v[40:43]
	ds_read_b128 v[116:119], v218 offset:51200
	s_add_u32 m0, s1, 8192
	s_nop 0
	global_load_lds_dwordx4 v226, s[84:85]
	s_waitcnt lgkmcnt(8)
	v_mfma_f32_16x16x32_bf16 v[12:15], v[72:75], v[92:95], v[12:15]
	v_mfma_f32_16x16x32_bf16 v[44:47], v[76:79], v[92:95], v[44:47]
	ds_read_b128 v[120:123], v218 offset:53248
	s_add_u32 m0, s1, 12288
	s_nop 0
	global_load_lds_dwordx4 v228, s[84:85]
	s_add_u32 s84, s84, 128
	s_addc_u32 s85, s85, 0
	s_waitcnt lgkmcnt(8)
	v_mfma_f32_16x16x32_bf16 v[16:19], v[72:75], v[96:99], v[16:19]
	v_mfma_f32_16x16x32_bf16 v[48:51], v[76:79], v[96:99], v[48:51]
	ds_read_b128 v[124:127], v218 offset:55296
	s_add_u32 m0, s1, 16384
	s_nop 0
	global_load_lds_dwordx4 v222, s[86:87]
	s_waitcnt lgkmcnt(8)
	v_mfma_f32_16x16x32_bf16 v[20:23], v[72:75], v[100:103], v[20:23]
	v_mfma_f32_16x16x32_bf16 v[52:55], v[76:79], v[100:103], v[52:55]
	ds_read_b128 v[80:83], v218 offset:57344
	s_add_u32 m0, s1, 20480
	s_nop 0
	global_load_lds_dwordx4 v224, s[86:87]
	s_waitcnt lgkmcnt(8)
	v_mfma_f32_16x16x32_bf16 v[24:27], v[72:75], v[104:107], v[24:27]
	v_mfma_f32_16x16x32_bf16 v[56:59], v[76:79], v[104:107], v[56:59]
	ds_read_b128 v[84:87], v218 offset:59392
	s_add_u32 m0, s1, 24576
	s_nop 0
	global_load_lds_dwordx4 v226, s[86:87]
	s_waitcnt lgkmcnt(8)
	v_mfma_f32_16x16x32_bf16 v[28:31], v[72:75], v[108:111], v[28:31]
	v_mfma_f32_16x16x32_bf16 v[60:63], v[76:79], v[108:111], v[60:63]
	ds_read_b128 v[88:91], v218 offset:61440
	s_add_u32 m0, s1, 28672
	s_nop 0
	global_load_lds_dwordx4 v228, s[86:87]
	s_add_u32 s86, s86, 128
	s_addc_u32 s87, s87, 0
	s_waitcnt lgkmcnt(6)
	v_mfma_f32_16x16x32_bf16 v[0:3], v[64:67], v[112:115], v[0:3]
	v_mfma_f32_16x16x32_bf16 v[32:35], v[68:71], v[112:115], v[32:35]
	ds_read_b128 v[92:95], v218 offset:63488
	s_waitcnt lgkmcnt(6)
	v_mfma_f32_16x16x32_bf16 v[4:7], v[64:67], v[116:119], v[4:7]
	v_mfma_f32_16x16x32_bf16 v[36:39], v[68:71], v[116:119], v[36:39]
	ds_read_b128 v[72:75], v216 offset:32768
	ds_read_b128 v[76:79], v216 offset:34816
	ds_read_b128 v[96:99], v220 offset:49152
	s_waitcnt lgkmcnt(8)
	v_mfma_f32_16x16x32_bf16 v[8:11], v[64:67], v[120:123], v[8:11]
	v_mfma_f32_16x16x32_bf16 v[40:43], v[68:71], v[120:123], v[40:43]
	ds_read_b128 v[100:103], v220 offset:51200
	s_waitcnt lgkmcnt(8)
	v_mfma_f32_16x16x32_bf16 v[12:15], v[64:67], v[124:127], v[12:15]
	v_mfma_f32_16x16x32_bf16 v[44:47], v[68:71], v[124:127], v[44:47]
	ds_read_b128 v[104:107], v220 offset:53248
	s_waitcnt lgkmcnt(8)
	v_mfma_f32_16x16x32_bf16 v[16:19], v[64:67], v[80:83], v[16:19]
	v_mfma_f32_16x16x32_bf16 v[48:51], v[68:71], v[80:83], v[48:51]
	ds_read_b128 v[108:111], v220 offset:55296
	s_waitcnt lgkmcnt(8)
	v_mfma_f32_16x16x32_bf16 v[20:23], v[64:67], v[84:87], v[20:23]
	v_mfma_f32_16x16x32_bf16 v[52:55], v[68:71], v[84:87], v[52:55]
	ds_read_b128 v[112:115], v220 offset:57344
	s_waitcnt lgkmcnt(8)
	v_mfma_f32_16x16x32_bf16 v[24:27], v[64:67], v[88:91], v[24:27]
	v_mfma_f32_16x16x32_bf16 v[56:59], v[68:71], v[88:91], v[56:59]
	ds_read_b128 v[116:119], v220 offset:59392
	s_waitcnt lgkmcnt(8)
	v_mfma_f32_16x16x32_bf16 v[28:31], v[64:67], v[92:95], v[28:31]
	v_mfma_f32_16x16x32_bf16 v[60:63], v[68:71], v[92:95], v[60:63]
	ds_read_b128 v[120:123], v220 offset:61440
	s_waitcnt lgkmcnt(6)
	v_mfma_f32_16x16x32_bf16 v[0:3], v[72:75], v[96:99], v[0:3]
	v_mfma_f32_16x16x32_bf16 v[32:35], v[76:79], v[96:99], v[32:35]
	ds_read_b128 v[124:127], v220 offset:63488
	s_waitcnt vmcnt(0) lgkmcnt(0)
	s_barrier
	s_add_u32 m0, s1, 32768
	s_nop 0
	global_load_lds_dwordx4 v222, s[84:85]
	s_waitcnt lgkmcnt(6)
	v_mfma_f32_16x16x32_bf16 v[4:7], v[72:75], v[100:103], v[4:7]
	v_mfma_f32_16x16x32_bf16 v[36:39], v[76:79], v[100:103], v[36:39]
	ds_read_b128 v[64:67], v142 offset:0
	ds_read_b128 v[68:71], v142 offset:2048
	ds_read_b128 v[80:83], v218 offset:16384
	s_add_u32 m0, s1, 36864
	s_nop 0
	global_load_lds_dwordx4 v224, s[84:85]
	s_waitcnt lgkmcnt(8)
	v_mfma_f32_16x16x32_bf16 v[8:11], v[72:75], v[104:107], v[8:11]
	v_mfma_f32_16x16x32_bf16 v[40:43], v[76:79], v[104:107], v[40:43]
	ds_read_b128 v[84:87], v218 offset:18432
	s_add_u32 m0, s1, 40960
	s_nop 0
	global_load_lds_dwordx4 v226, s[84:85]
	s_waitcnt lgkmcnt(8)
	v_mfma_f32_16x16x32_bf16 v[12:15], v[72:75], v[108:111], v[12:15]
	v_mfma_f32_16x16x32_bf16 v[44:47], v[76:79], v[108:111], v[44:47]
	ds_read_b128 v[88:91], v218 offset:20480
	s_add_u32 m0, s1, 45056
	s_nop 0
	global_load_lds_dwordx4 v228, s[84:85]
	s_add_u32 s84, s84, 128
	s_addc_u32 s85, s85, 0
	s_waitcnt lgkmcnt(8)
	v_mfma_f32_16x16x32_bf16 v[16:19], v[72:75], v[112:115], v[16:19]
	v_mfma_f32_16x16x32_bf16 v[48:51], v[76:79], v[112:115], v[48:51]
	ds_read_b128 v[92:95], v218 offset:22528
	s_add_u32 m0, s1, 49152
	s_nop 0
	global_load_lds_dwordx4 v222, s[86:87]
	s_waitcnt lgkmcnt(8)
	v_mfma_f32_16x16x32_bf16 v[20:23], v[72:75], v[116:119], v[20:23]
	v_mfma_f32_16x16x32_bf16 v[52:55], v[76:79], v[116:119], v[52:55]
	ds_read_b128 v[96:99], v218 offset:24576
	s_add_u32 m0, s1, 53248
	s_nop 0
	global_load_lds_dwordx4 v224, s[86:87]
	s_waitcnt lgkmcnt(8)
	v_mfma_f32_16x16x32_bf16 v[24:27], v[72:75], v[120:123], v[24:27]
	v_mfma_f32_16x16x32_bf16 v[56:59], v[76:79], v[120:123], v[56:59]
	ds_read_b128 v[100:103], v218 offset:26624
	s_add_u32 m0, s1, 57344
	s_nop 0
	global_load_lds_dwordx4 v226, s[86:87]
	s_waitcnt lgkmcnt(8)
	v_mfma_f32_16x16x32_bf16 v[28:31], v[72:75], v[124:127], v[28:31]
	v_mfma_f32_16x16x32_bf16 v[60:63], v[76:79], v[124:127], v[60:63]
	ds_read_b128 v[104:107], v218 offset:28672
	s_add_u32 m0, s1, 61440
	s_nop 0
	global_load_lds_dwordx4 v228, s[86:87]
	s_add_u32 s86, s86, 128
	s_addc_u32 s87, s87, 0
	s_waitcnt lgkmcnt(6)
	v_mfma_f32_16x16x32_bf16 v[0:3], v[64:67], v[80:83], v[0:3]
	v_mfma_f32_16x16x32_bf16 v[32:35], v[68:71], v[80:83], v[32:35]
	ds_read_b128 v[108:111], v218 offset:30720
	s_waitcnt lgkmcnt(6)
	v_mfma_f32_16x16x32_bf16 v[4:7], v[64:67], v[84:87], v[4:7]
	v_mfma_f32_16x16x32_bf16 v[36:39], v[68:71], v[84:87], v[36:39]
	ds_read_b128 v[72:75], v216 offset:0
	ds_read_b128 v[76:79], v216 offset:2048
	ds_read_b128 v[112:115], v220 offset:16384
	s_waitcnt lgkmcnt(8)
	v_mfma_f32_16x16x32_bf16 v[8:11], v[64:67], v[88:91], v[8:11]
	v_mfma_f32_16x16x32_bf16 v[40:43], v[68:71], v[88:91], v[40:43]
	ds_read_b128 v[116:119], v220 offset:18432
	s_waitcnt lgkmcnt(8)
	v_mfma_f32_16x16x32_bf16 v[12:15], v[64:67], v[92:95], v[12:15]
	v_mfma_f32_16x16x32_bf16 v[44:47], v[68:71], v[92:95], v[44:47]
	ds_read_b128 v[120:123], v220 offset:20480
	s_waitcnt lgkmcnt(8)
	v_mfma_f32_16x16x32_bf16 v[16:19], v[64:67], v[96:99], v[16:19]
	v_mfma_f32_16x16x32_bf16 v[48:51], v[68:71], v[96:99], v[48:51]
	ds_read_b128 v[124:127], v220 offset:22528
	s_waitcnt lgkmcnt(8)
	v_mfma_f32_16x16x32_bf16 v[20:23], v[64:67], v[100:103], v[20:23]
	v_mfma_f32_16x16x32_bf16 v[52:55], v[68:71], v[100:103], v[52:55]
	ds_read_b128 v[80:83], v220 offset:24576
	s_waitcnt lgkmcnt(8)
	v_mfma_f32_16x16x32_bf16 v[24:27], v[64:67], v[104:107], v[24:27]
	v_mfma_f32_16x16x32_bf16 v[56:59], v[68:71], v[104:107], v[56:59]
	ds_read_b128 v[84:87], v220 offset:26624
	s_waitcnt lgkmcnt(8)
	v_mfma_f32_16x16x32_bf16 v[28:31], v[64:67], v[108:111], v[28:31]
	v_mfma_f32_16x16x32_bf16 v[60:63], v[68:71], v[108:111], v[60:63]
	ds_read_b128 v[88:91], v220 offset:28672
	s_waitcnt lgkmcnt(6)
	v_mfma_f32_16x16x32_bf16 v[0:3], v[72:75], v[112:115], v[0:3]
	v_mfma_f32_16x16x32_bf16 v[32:35], v[76:79], v[112:115], v[32:35]
	ds_read_b128 v[92:95], v220 offset:30720
	s_waitcnt vmcnt(0) lgkmcnt(0)
	s_barrier
	s_add_u32 m0, s1, 0
	s_nop 0
	global_load_lds_dwordx4 v222, s[84:85]
	s_waitcnt lgkmcnt(6)
	v_mfma_f32_16x16x32_bf16 v[4:7], v[72:75], v[116:119], v[4:7]
	v_mfma_f32_16x16x32_bf16 v[36:39], v[76:79], v[116:119], v[36:39]
	ds_read_b128 v[64:67], v142 offset:32768
	ds_read_b128 v[68:71], v142 offset:34816
	ds_read_b128 v[96:99], v218 offset:49152
	s_add_u32 m0, s1, 4096
	s_nop 0
	global_load_lds_dwordx4 v224, s[84:85]
	s_waitcnt lgkmcnt(8)
	v_mfma_f32_16x16x32_bf16 v[8:11], v[72:75], v[120:123], v[8:11]
	v_mfma_f32_16x16x32_bf16 v[40:43], v[76:79], v[120:123], v[40:43]
	ds_read_b128 v[100:103], v218 offset:51200
	s_add_u32 m0, s1, 8192
	s_nop 0
	global_load_lds_dwordx4 v226, s[84:85]
	s_waitcnt lgkmcnt(8)
	v_mfma_f32_16x16x32_bf16 v[12:15], v[72:75], v[124:127], v[12:15]
	v_mfma_f32_16x16x32_bf16 v[44:47], v[76:79], v[124:127], v[44:47]
	ds_read_b128 v[104:107], v218 offset:53248
	s_add_u32 m0, s1, 12288
	s_nop 0
	global_load_lds_dwordx4 v228, s[84:85]
	s_add_u32 s84, s84, 128
	s_addc_u32 s85, s85, 0
	s_waitcnt lgkmcnt(8)
	v_mfma_f32_16x16x32_bf16 v[16:19], v[72:75], v[80:83], v[16:19]
	v_mfma_f32_16x16x32_bf16 v[48:51], v[76:79], v[80:83], v[48:51]
	ds_read_b128 v[108:111], v218 offset:55296
	s_add_u32 m0, s1, 16384
	s_nop 0
	global_load_lds_dwordx4 v222, s[86:87]
	s_waitcnt lgkmcnt(8)
	v_mfma_f32_16x16x32_bf16 v[20:23], v[72:75], v[84:87], v[20:23]
	v_mfma_f32_16x16x32_bf16 v[52:55], v[76:79], v[84:87], v[52:55]
	ds_read_b128 v[112:115], v218 offset:57344
	s_add_u32 m0, s1, 20480
	s_nop 0
	global_load_lds_dwordx4 v224, s[86:87]
	s_waitcnt lgkmcnt(8)
	v_mfma_f32_16x16x32_bf16 v[24:27], v[72:75], v[88:91], v[24:27]
	v_mfma_f32_16x16x32_bf16 v[56:59], v[76:79], v[88:91], v[56:59]
	ds_read_b128 v[116:119], v218 offset:59392
	s_add_u32 m0, s1, 24576
	s_nop 0
	global_load_lds_dwordx4 v226, s[86:87]
	s_waitcnt lgkmcnt(8)
	v_mfma_f32_16x16x32_bf16 v[28:31], v[72:75], v[92:95], v[28:31]
	v_mfma_f32_16x16x32_bf16 v[60:63], v[76:79], v[92:95], v[60:63]
	ds_read_b128 v[120:123], v218 offset:61440
	s_add_u32 m0, s1, 28672
	s_nop 0
	global_load_lds_dwordx4 v228, s[86:87]
	s_add_u32 s86, s86, 128
	s_addc_u32 s87, s87, 0
	s_waitcnt lgkmcnt(6)
	v_mfma_f32_16x16x32_bf16 v[0:3], v[64:67], v[96:99], v[0:3]
	v_mfma_f32_16x16x32_bf16 v[32:35], v[68:71], v[96:99], v[32:35]
	ds_read_b128 v[124:127], v218 offset:63488
	s_waitcnt lgkmcnt(6)
	v_mfma_f32_16x16x32_bf16 v[4:7], v[64:67], v[100:103], v[4:7]
	v_mfma_f32_16x16x32_bf16 v[36:39], v[68:71], v[100:103], v[36:39]
	ds_read_b128 v[72:75], v216 offset:32768
	ds_read_b128 v[76:79], v216 offset:34816
	ds_read_b128 v[80:83], v220 offset:49152
	s_waitcnt lgkmcnt(8)
	v_mfma_f32_16x16x32_bf16 v[8:11], v[64:67], v[104:107], v[8:11]
	v_mfma_f32_16x16x32_bf16 v[40:43], v[68:71], v[104:107], v[40:43]
	ds_read_b128 v[84:87], v220 offset:51200
	s_waitcnt lgkmcnt(8)
	v_mfma_f32_16x16x32_bf16 v[12:15], v[64:67], v[108:111], v[12:15]
	v_mfma_f32_16x16x32_bf16 v[44:47], v[68:71], v[108:111], v[44:47]
	ds_read_b128 v[88:91], v220 offset:53248
	s_waitcnt lgkmcnt(8)
	v_mfma_f32_16x16x32_bf16 v[16:19], v[64:67], v[112:115], v[16:19]
	v_mfma_f32_16x16x32_bf16 v[48:51], v[68:71], v[112:115], v[48:51]
	ds_read_b128 v[92:95], v220 offset:55296
	s_waitcnt lgkmcnt(8)
	v_mfma_f32_16x16x32_bf16 v[20:23], v[64:67], v[116:119], v[20:23]
	v_mfma_f32_16x16x32_bf16 v[52:55], v[68:71], v[116:119], v[52:55]
	ds_read_b128 v[96:99], v220 offset:57344
	s_waitcnt lgkmcnt(8)
	v_mfma_f32_16x16x32_bf16 v[24:27], v[64:67], v[120:123], v[24:27]
	v_mfma_f32_16x16x32_bf16 v[56:59], v[68:71], v[120:123], v[56:59]
	ds_read_b128 v[100:103], v220 offset:59392
	s_waitcnt lgkmcnt(8)
	v_mfma_f32_16x16x32_bf16 v[28:31], v[64:67], v[124:127], v[28:31]
	v_mfma_f32_16x16x32_bf16 v[60:63], v[68:71], v[124:127], v[60:63]
	ds_read_b128 v[104:107], v220 offset:61440
	s_waitcnt lgkmcnt(6)
	v_mfma_f32_16x16x32_bf16 v[0:3], v[72:75], v[80:83], v[0:3]
	v_mfma_f32_16x16x32_bf16 v[32:35], v[76:79], v[80:83], v[32:35]
	ds_read_b128 v[108:111], v220 offset:63488
	s_waitcnt vmcnt(0) lgkmcnt(0)
	s_barrier
	s_add_u32 m0, s1, 32768
	s_nop 0
	global_load_lds_dwordx4 v222, s[84:85]
	s_waitcnt lgkmcnt(6)
	v_mfma_f32_16x16x32_bf16 v[4:7], v[72:75], v[84:87], v[4:7]
	v_mfma_f32_16x16x32_bf16 v[36:39], v[76:79], v[84:87], v[36:39]
	ds_read_b128 v[64:67], v142 offset:0
	ds_read_b128 v[68:71], v142 offset:2048
	ds_read_b128 v[112:115], v218 offset:16384
	s_add_u32 m0, s1, 36864
	s_nop 0
	global_load_lds_dwordx4 v224, s[84:85]
	s_waitcnt lgkmcnt(8)
	v_mfma_f32_16x16x32_bf16 v[8:11], v[72:75], v[88:91], v[8:11]
	v_mfma_f32_16x16x32_bf16 v[40:43], v[76:79], v[88:91], v[40:43]
	ds_read_b128 v[116:119], v218 offset:18432
	s_add_u32 m0, s1, 40960
	s_nop 0
	global_load_lds_dwordx4 v226, s[84:85]
	s_waitcnt lgkmcnt(8)
	v_mfma_f32_16x16x32_bf16 v[12:15], v[72:75], v[92:95], v[12:15]
	v_mfma_f32_16x16x32_bf16 v[44:47], v[76:79], v[92:95], v[44:47]
	ds_read_b128 v[120:123], v218 offset:20480
	s_add_u32 m0, s1, 45056
	s_nop 0
	global_load_lds_dwordx4 v228, s[84:85]
	s_add_u32 s84, s84, 128
	s_addc_u32 s85, s85, 0
	s_waitcnt lgkmcnt(8)
	v_mfma_f32_16x16x32_bf16 v[16:19], v[72:75], v[96:99], v[16:19]
	v_mfma_f32_16x16x32_bf16 v[48:51], v[76:79], v[96:99], v[48:51]
	ds_read_b128 v[124:127], v218 offset:22528
	s_add_u32 m0, s1, 49152
	s_nop 0
	global_load_lds_dwordx4 v222, s[86:87]
	s_waitcnt lgkmcnt(8)
	v_mfma_f32_16x16x32_bf16 v[20:23], v[72:75], v[100:103], v[20:23]
	v_mfma_f32_16x16x32_bf16 v[52:55], v[76:79], v[100:103], v[52:55]
	ds_read_b128 v[80:83], v218 offset:24576
	s_add_u32 m0, s1, 53248
	s_nop 0
	global_load_lds_dwordx4 v224, s[86:87]
	s_waitcnt lgkmcnt(8)
	v_mfma_f32_16x16x32_bf16 v[24:27], v[72:75], v[104:107], v[24:27]
	v_mfma_f32_16x16x32_bf16 v[56:59], v[76:79], v[104:107], v[56:59]
	ds_read_b128 v[84:87], v218 offset:26624
	s_add_u32 m0, s1, 57344
	s_nop 0
	global_load_lds_dwordx4 v226, s[86:87]
	s_waitcnt lgkmcnt(8)
	v_mfma_f32_16x16x32_bf16 v[28:31], v[72:75], v[108:111], v[28:31]
	v_mfma_f32_16x16x32_bf16 v[60:63], v[76:79], v[108:111], v[60:63]
	ds_read_b128 v[88:91], v218 offset:28672
	s_add_u32 m0, s1, 61440
	s_nop 0
	global_load_lds_dwordx4 v228, s[86:87]
	s_add_u32 s86, s86, 128
	s_addc_u32 s87, s87, 0
	s_waitcnt lgkmcnt(6)
	v_mfma_f32_16x16x32_bf16 v[0:3], v[64:67], v[112:115], v[0:3]
	v_mfma_f32_16x16x32_bf16 v[32:35], v[68:71], v[112:115], v[32:35]
	ds_read_b128 v[92:95], v218 offset:30720
	s_waitcnt lgkmcnt(6)
	v_mfma_f32_16x16x32_bf16 v[4:7], v[64:67], v[116:119], v[4:7]
	v_mfma_f32_16x16x32_bf16 v[36:39], v[68:71], v[116:119], v[36:39]
	ds_read_b128 v[72:75], v216 offset:0
	ds_read_b128 v[76:79], v216 offset:2048
	ds_read_b128 v[96:99], v220 offset:16384
	s_waitcnt lgkmcnt(8)
	v_mfma_f32_16x16x32_bf16 v[8:11], v[64:67], v[120:123], v[8:11]
	v_mfma_f32_16x16x32_bf16 v[40:43], v[68:71], v[120:123], v[40:43]
	ds_read_b128 v[100:103], v220 offset:18432
	s_waitcnt lgkmcnt(8)
	v_mfma_f32_16x16x32_bf16 v[12:15], v[64:67], v[124:127], v[12:15]
	v_mfma_f32_16x16x32_bf16 v[44:47], v[68:71], v[124:127], v[44:47]
	ds_read_b128 v[104:107], v220 offset:20480
	s_waitcnt lgkmcnt(8)
	v_mfma_f32_16x16x32_bf16 v[16:19], v[64:67], v[80:83], v[16:19]
	v_mfma_f32_16x16x32_bf16 v[48:51], v[68:71], v[80:83], v[48:51]
	ds_read_b128 v[108:111], v220 offset:22528
	s_waitcnt lgkmcnt(8)
	v_mfma_f32_16x16x32_bf16 v[20:23], v[64:67], v[84:87], v[20:23]
	v_mfma_f32_16x16x32_bf16 v[52:55], v[68:71], v[84:87], v[52:55]
	ds_read_b128 v[112:115], v220 offset:24576
	s_waitcnt lgkmcnt(8)
	v_mfma_f32_16x16x32_bf16 v[24:27], v[64:67], v[88:91], v[24:27]
	v_mfma_f32_16x16x32_bf16 v[56:59], v[68:71], v[88:91], v[56:59]
	ds_read_b128 v[116:119], v220 offset:26624
	s_waitcnt lgkmcnt(8)
	v_mfma_f32_16x16x32_bf16 v[28:31], v[64:67], v[92:95], v[28:31]
	v_mfma_f32_16x16x32_bf16 v[60:63], v[68:71], v[92:95], v[60:63]
	ds_read_b128 v[120:123], v220 offset:28672
	s_waitcnt lgkmcnt(6)
	v_mfma_f32_16x16x32_bf16 v[0:3], v[72:75], v[96:99], v[0:3]
	v_mfma_f32_16x16x32_bf16 v[32:35], v[76:79], v[96:99], v[32:35]
	ds_read_b128 v[124:127], v220 offset:30720
	s_waitcnt vmcnt(0) lgkmcnt(0)
	s_barrier
	s_add_u32 m0, s1, 0
	s_nop 0
	global_load_lds_dwordx4 v222, s[84:85]
	s_waitcnt lgkmcnt(6)
	v_mfma_f32_16x16x32_bf16 v[4:7], v[72:75], v[100:103], v[4:7]
	v_mfma_f32_16x16x32_bf16 v[36:39], v[76:79], v[100:103], v[36:39]
	ds_read_b128 v[64:67], v142 offset:32768
	ds_read_b128 v[68:71], v142 offset:34816
	ds_read_b128 v[80:83], v218 offset:49152
	s_add_u32 m0, s1, 4096
	s_nop 0
	global_load_lds_dwordx4 v224, s[84:85]
	s_waitcnt lgkmcnt(8)
	v_mfma_f32_16x16x32_bf16 v[8:11], v[72:75], v[104:107], v[8:11]
	v_mfma_f32_16x16x32_bf16 v[40:43], v[76:79], v[104:107], v[40:43]
	ds_read_b128 v[84:87], v218 offset:51200
	s_add_u32 m0, s1, 8192
	s_nop 0
	global_load_lds_dwordx4 v226, s[84:85]
	s_waitcnt lgkmcnt(8)
	v_mfma_f32_16x16x32_bf16 v[12:15], v[72:75], v[108:111], v[12:15]
	v_mfma_f32_16x16x32_bf16 v[44:47], v[76:79], v[108:111], v[44:47]
	ds_read_b128 v[88:91], v218 offset:53248
	s_add_u32 m0, s1, 12288
	s_nop 0
	global_load_lds_dwordx4 v228, s[84:85]
	s_add_u32 s84, s84, 128
	s_addc_u32 s85, s85, 0
	s_waitcnt lgkmcnt(8)
	v_mfma_f32_16x16x32_bf16 v[16:19], v[72:75], v[112:115], v[16:19]
	v_mfma_f32_16x16x32_bf16 v[48:51], v[76:79], v[112:115], v[48:51]
	ds_read_b128 v[92:95], v218 offset:55296
	s_add_u32 m0, s1, 16384
	s_nop 0
	global_load_lds_dwordx4 v222, s[86:87]
	s_waitcnt lgkmcnt(8)
	v_mfma_f32_16x16x32_bf16 v[20:23], v[72:75], v[116:119], v[20:23]
	v_mfma_f32_16x16x32_bf16 v[52:55], v[76:79], v[116:119], v[52:55]
	ds_read_b128 v[96:99], v218 offset:57344
	s_add_u32 m0, s1, 20480
	s_nop 0
	global_load_lds_dwordx4 v224, s[86:87]
	s_waitcnt lgkmcnt(8)
	v_mfma_f32_16x16x32_bf16 v[24:27], v[72:75], v[120:123], v[24:27]
	v_mfma_f32_16x16x32_bf16 v[56:59], v[76:79], v[120:123], v[56:59]
	ds_read_b128 v[100:103], v218 offset:59392
	s_add_u32 m0, s1, 24576
	s_nop 0
	global_load_lds_dwordx4 v226, s[86:87]
	s_waitcnt lgkmcnt(8)
	v_mfma_f32_16x16x32_bf16 v[28:31], v[72:75], v[124:127], v[28:31]
	v_mfma_f32_16x16x32_bf16 v[60:63], v[76:79], v[124:127], v[60:63]
	ds_read_b128 v[104:107], v218 offset:61440
	s_add_u32 m0, s1, 28672
	s_nop 0
	global_load_lds_dwordx4 v228, s[86:87]
	s_add_u32 s86, s86, 128
	s_addc_u32 s87, s87, 0
	s_waitcnt lgkmcnt(6)
	v_mfma_f32_16x16x32_bf16 v[0:3], v[64:67], v[80:83], v[0:3]
	v_mfma_f32_16x16x32_bf16 v[32:35], v[68:71], v[80:83], v[32:35]
	ds_read_b128 v[108:111], v218 offset:63488
	s_waitcnt lgkmcnt(6)
	v_mfma_f32_16x16x32_bf16 v[4:7], v[64:67], v[84:87], v[4:7]
	v_mfma_f32_16x16x32_bf16 v[36:39], v[68:71], v[84:87], v[36:39]
	ds_read_b128 v[72:75], v216 offset:32768
	ds_read_b128 v[76:79], v216 offset:34816
	ds_read_b128 v[112:115], v220 offset:49152
	s_waitcnt lgkmcnt(8)
	v_mfma_f32_16x16x32_bf16 v[8:11], v[64:67], v[88:91], v[8:11]
	v_mfma_f32_16x16x32_bf16 v[40:43], v[68:71], v[88:91], v[40:43]
	ds_read_b128 v[116:119], v220 offset:51200
	s_waitcnt lgkmcnt(8)
	v_mfma_f32_16x16x32_bf16 v[12:15], v[64:67], v[92:95], v[12:15]
	v_mfma_f32_16x16x32_bf16 v[44:47], v[68:71], v[92:95], v[44:47]
	ds_read_b128 v[120:123], v220 offset:53248
	s_waitcnt lgkmcnt(8)
	v_mfma_f32_16x16x32_bf16 v[16:19], v[64:67], v[96:99], v[16:19]
	v_mfma_f32_16x16x32_bf16 v[48:51], v[68:71], v[96:99], v[48:51]
	ds_read_b128 v[124:127], v220 offset:55296
	s_waitcnt lgkmcnt(8)
	v_mfma_f32_16x16x32_bf16 v[20:23], v[64:67], v[100:103], v[20:23]
	v_mfma_f32_16x16x32_bf16 v[52:55], v[68:71], v[100:103], v[52:55]
	ds_read_b128 v[80:83], v220 offset:57344
	s_waitcnt lgkmcnt(8)
	v_mfma_f32_16x16x32_bf16 v[24:27], v[64:67], v[104:107], v[24:27]
	v_mfma_f32_16x16x32_bf16 v[56:59], v[68:71], v[104:107], v[56:59]
	ds_read_b128 v[84:87], v220 offset:59392
	s_waitcnt lgkmcnt(8)
	v_mfma_f32_16x16x32_bf16 v[28:31], v[64:67], v[108:111], v[28:31]
	v_mfma_f32_16x16x32_bf16 v[60:63], v[68:71], v[108:111], v[60:63]
	ds_read_b128 v[88:91], v220 offset:61440
	s_waitcnt lgkmcnt(6)
	v_mfma_f32_16x16x32_bf16 v[0:3], v[72:75], v[112:115], v[0:3]
	v_mfma_f32_16x16x32_bf16 v[32:35], v[76:79], v[112:115], v[32:35]
	ds_read_b128 v[92:95], v220 offset:63488
	s_waitcnt vmcnt(0) lgkmcnt(0)
	s_barrier
	s_add_u32 m0, s1, 32768
	s_nop 0
	global_load_lds_dwordx4 v222, s[84:85]
	s_waitcnt lgkmcnt(6)
	v_mfma_f32_16x16x32_bf16 v[4:7], v[72:75], v[116:119], v[4:7]
	v_mfma_f32_16x16x32_bf16 v[36:39], v[76:79], v[116:119], v[36:39]
	ds_read_b128 v[64:67], v142 offset:0
	ds_read_b128 v[68:71], v142 offset:2048
	ds_read_b128 v[96:99], v218 offset:16384
	s_add_u32 m0, s1, 36864
	s_nop 0
	global_load_lds_dwordx4 v224, s[84:85]
	s_waitcnt lgkmcnt(8)
	v_mfma_f32_16x16x32_bf16 v[8:11], v[72:75], v[120:123], v[8:11]
	v_mfma_f32_16x16x32_bf16 v[40:43], v[76:79], v[120:123], v[40:43]
	ds_read_b128 v[100:103], v218 offset:18432
	s_add_u32 m0, s1, 40960
	s_nop 0
	global_load_lds_dwordx4 v226, s[84:85]
	s_waitcnt lgkmcnt(8)
	v_mfma_f32_16x16x32_bf16 v[12:15], v[72:75], v[124:127], v[12:15]
	v_mfma_f32_16x16x32_bf16 v[44:47], v[76:79], v[124:127], v[44:47]
	ds_read_b128 v[104:107], v218 offset:20480
	s_add_u32 m0, s1, 45056
	s_nop 0
	global_load_lds_dwordx4 v228, s[84:85]
	s_add_u32 s84, s84, 128
	s_addc_u32 s85, s85, 0
	s_waitcnt lgkmcnt(8)
	v_mfma_f32_16x16x32_bf16 v[16:19], v[72:75], v[80:83], v[16:19]
	v_mfma_f32_16x16x32_bf16 v[48:51], v[76:79], v[80:83], v[48:51]
	ds_read_b128 v[108:111], v218 offset:22528
	s_add_u32 m0, s1, 49152
	s_nop 0
	global_load_lds_dwordx4 v222, s[86:87]
	s_waitcnt lgkmcnt(8)
	v_mfma_f32_16x16x32_bf16 v[20:23], v[72:75], v[84:87], v[20:23]
	v_mfma_f32_16x16x32_bf16 v[52:55], v[76:79], v[84:87], v[52:55]
	ds_read_b128 v[112:115], v218 offset:24576
	s_add_u32 m0, s1, 53248
	s_nop 0
	global_load_lds_dwordx4 v224, s[86:87]
	s_waitcnt lgkmcnt(8)
	v_mfma_f32_16x16x32_bf16 v[24:27], v[72:75], v[88:91], v[24:27]
	v_mfma_f32_16x16x32_bf16 v[56:59], v[76:79], v[88:91], v[56:59]
	ds_read_b128 v[116:119], v218 offset:26624
	s_add_u32 m0, s1, 57344
	s_nop 0
	global_load_lds_dwordx4 v226, s[86:87]
	s_waitcnt lgkmcnt(8)
	v_mfma_f32_16x16x32_bf16 v[28:31], v[72:75], v[92:95], v[28:31]
	v_mfma_f32_16x16x32_bf16 v[60:63], v[76:79], v[92:95], v[60:63]
	ds_read_b128 v[120:123], v218 offset:28672
	s_add_u32 m0, s1, 61440
	s_nop 0
	global_load_lds_dwordx4 v228, s[86:87]
	s_add_u32 s86, s86, 128
	s_addc_u32 s87, s87, 0
	s_waitcnt lgkmcnt(6)
	v_mfma_f32_16x16x32_bf16 v[0:3], v[64:67], v[96:99], v[0:3]
	v_mfma_f32_16x16x32_bf16 v[32:35], v[68:71], v[96:99], v[32:35]
	ds_read_b128 v[124:127], v218 offset:30720
	s_waitcnt lgkmcnt(6)
	v_mfma_f32_16x16x32_bf16 v[4:7], v[64:67], v[100:103], v[4:7]
	v_mfma_f32_16x16x32_bf16 v[36:39], v[68:71], v[100:103], v[36:39]
	ds_read_b128 v[72:75], v216 offset:0
	ds_read_b128 v[76:79], v216 offset:2048
	ds_read_b128 v[80:83], v220 offset:16384
	s_waitcnt lgkmcnt(8)
	v_mfma_f32_16x16x32_bf16 v[8:11], v[64:67], v[104:107], v[8:11]
	v_mfma_f32_16x16x32_bf16 v[40:43], v[68:71], v[104:107], v[40:43]
	ds_read_b128 v[84:87], v220 offset:18432
	s_waitcnt lgkmcnt(8)
	v_mfma_f32_16x16x32_bf16 v[12:15], v[64:67], v[108:111], v[12:15]
	v_mfma_f32_16x16x32_bf16 v[44:47], v[68:71], v[108:111], v[44:47]
	ds_read_b128 v[88:91], v220 offset:20480
	s_waitcnt lgkmcnt(8)
	v_mfma_f32_16x16x32_bf16 v[16:19], v[64:67], v[112:115], v[16:19]
	v_mfma_f32_16x16x32_bf16 v[48:51], v[68:71], v[112:115], v[48:51]
	ds_read_b128 v[92:95], v220 offset:22528
	s_waitcnt lgkmcnt(8)
	v_mfma_f32_16x16x32_bf16 v[20:23], v[64:67], v[116:119], v[20:23]
	v_mfma_f32_16x16x32_bf16 v[52:55], v[68:71], v[116:119], v[52:55]
	ds_read_b128 v[96:99], v220 offset:24576
	s_waitcnt lgkmcnt(8)
	v_mfma_f32_16x16x32_bf16 v[24:27], v[64:67], v[120:123], v[24:27]
	v_mfma_f32_16x16x32_bf16 v[56:59], v[68:71], v[120:123], v[56:59]
	ds_read_b128 v[100:103], v220 offset:26624
	s_waitcnt lgkmcnt(8)
	v_mfma_f32_16x16x32_bf16 v[28:31], v[64:67], v[124:127], v[28:31]
	v_mfma_f32_16x16x32_bf16 v[60:63], v[68:71], v[124:127], v[60:63]
	ds_read_b128 v[104:107], v220 offset:28672
	s_waitcnt lgkmcnt(6)
	v_mfma_f32_16x16x32_bf16 v[0:3], v[72:75], v[80:83], v[0:3]
	v_mfma_f32_16x16x32_bf16 v[32:35], v[76:79], v[80:83], v[32:35]
	ds_read_b128 v[108:111], v220 offset:30720
	s_waitcnt vmcnt(0) lgkmcnt(0)
	s_barrier
	s_add_u32 m0, s1, 0
	s_nop 0
	global_load_lds_dwordx4 v222, s[84:85]
	s_waitcnt lgkmcnt(6)
	v_mfma_f32_16x16x32_bf16 v[4:7], v[72:75], v[84:87], v[4:7]
	v_mfma_f32_16x16x32_bf16 v[36:39], v[76:79], v[84:87], v[36:39]
	ds_read_b128 v[64:67], v142 offset:32768
	ds_read_b128 v[68:71], v142 offset:34816
	ds_read_b128 v[112:115], v218 offset:49152
	s_add_u32 m0, s1, 4096
	s_nop 0
	global_load_lds_dwordx4 v224, s[84:85]
	s_waitcnt lgkmcnt(8)
	v_mfma_f32_16x16x32_bf16 v[8:11], v[72:75], v[88:91], v[8:11]
	v_mfma_f32_16x16x32_bf16 v[40:43], v[76:79], v[88:91], v[40:43]
	ds_read_b128 v[116:119], v218 offset:51200
	s_add_u32 m0, s1, 8192
	s_nop 0
	global_load_lds_dwordx4 v226, s[84:85]
	s_waitcnt lgkmcnt(8)
	v_mfma_f32_16x16x32_bf16 v[12:15], v[72:75], v[92:95], v[12:15]
	v_mfma_f32_16x16x32_bf16 v[44:47], v[76:79], v[92:95], v[44:47]
	ds_read_b128 v[120:123], v218 offset:53248
	s_add_u32 m0, s1, 12288
	s_nop 0
	global_load_lds_dwordx4 v228, s[84:85]
	s_add_u32 s84, s84, 128
	s_addc_u32 s85, s85, 0
	s_waitcnt lgkmcnt(8)
	v_mfma_f32_16x16x32_bf16 v[16:19], v[72:75], v[96:99], v[16:19]
	v_mfma_f32_16x16x32_bf16 v[48:51], v[76:79], v[96:99], v[48:51]
	ds_read_b128 v[124:127], v218 offset:55296
	s_add_u32 m0, s1, 16384
	s_nop 0
	global_load_lds_dwordx4 v222, s[86:87]
	s_waitcnt lgkmcnt(8)
	v_mfma_f32_16x16x32_bf16 v[20:23], v[72:75], v[100:103], v[20:23]
	v_mfma_f32_16x16x32_bf16 v[52:55], v[76:79], v[100:103], v[52:55]
	ds_read_b128 v[80:83], v218 offset:57344
	s_add_u32 m0, s1, 20480
	s_nop 0
	global_load_lds_dwordx4 v224, s[86:87]
	s_waitcnt lgkmcnt(8)
	v_mfma_f32_16x16x32_bf16 v[24:27], v[72:75], v[104:107], v[24:27]
	v_mfma_f32_16x16x32_bf16 v[56:59], v[76:79], v[104:107], v[56:59]
	ds_read_b128 v[84:87], v218 offset:59392
	s_add_u32 m0, s1, 24576
	s_nop 0
	global_load_lds_dwordx4 v226, s[86:87]
	s_waitcnt lgkmcnt(8)
	v_mfma_f32_16x16x32_bf16 v[28:31], v[72:75], v[108:111], v[28:31]
	v_mfma_f32_16x16x32_bf16 v[60:63], v[76:79], v[108:111], v[60:63]
	ds_read_b128 v[88:91], v218 offset:61440
	s_add_u32 m0, s1, 28672
	s_nop 0
	global_load_lds_dwordx4 v228, s[86:87]
	s_add_u32 s86, s86, 128
	s_addc_u32 s87, s87, 0
	s_waitcnt lgkmcnt(6)
	v_mfma_f32_16x16x32_bf16 v[0:3], v[64:67], v[112:115], v[0:3]
	v_mfma_f32_16x16x32_bf16 v[32:35], v[68:71], v[112:115], v[32:35]
	ds_read_b128 v[92:95], v218 offset:63488
	s_waitcnt lgkmcnt(6)
	v_mfma_f32_16x16x32_bf16 v[4:7], v[64:67], v[116:119], v[4:7]
	v_mfma_f32_16x16x32_bf16 v[36:39], v[68:71], v[116:119], v[36:39]
	ds_read_b128 v[72:75], v216 offset:32768
	ds_read_b128 v[76:79], v216 offset:34816
	ds_read_b128 v[96:99], v220 offset:49152
	s_waitcnt lgkmcnt(8)
	v_mfma_f32_16x16x32_bf16 v[8:11], v[64:67], v[120:123], v[8:11]
	v_mfma_f32_16x16x32_bf16 v[40:43], v[68:71], v[120:123], v[40:43]
	ds_read_b128 v[100:103], v220 offset:51200
	s_waitcnt lgkmcnt(8)
	v_mfma_f32_16x16x32_bf16 v[12:15], v[64:67], v[124:127], v[12:15]
	v_mfma_f32_16x16x32_bf16 v[44:47], v[68:71], v[124:127], v[44:47]
	ds_read_b128 v[104:107], v220 offset:53248
	s_waitcnt lgkmcnt(8)
	v_mfma_f32_16x16x32_bf16 v[16:19], v[64:67], v[80:83], v[16:19]
	v_mfma_f32_16x16x32_bf16 v[48:51], v[68:71], v[80:83], v[48:51]
	ds_read_b128 v[108:111], v220 offset:55296
	s_waitcnt lgkmcnt(8)
	v_mfma_f32_16x16x32_bf16 v[20:23], v[64:67], v[84:87], v[20:23]
	v_mfma_f32_16x16x32_bf16 v[52:55], v[68:71], v[84:87], v[52:55]
	ds_read_b128 v[112:115], v220 offset:57344
	s_waitcnt lgkmcnt(8)
	v_mfma_f32_16x16x32_bf16 v[24:27], v[64:67], v[88:91], v[24:27]
	v_mfma_f32_16x16x32_bf16 v[56:59], v[68:71], v[88:91], v[56:59]
	ds_read_b128 v[116:119], v220 offset:59392
	s_waitcnt lgkmcnt(8)
	v_mfma_f32_16x16x32_bf16 v[28:31], v[64:67], v[92:95], v[28:31]
	v_mfma_f32_16x16x32_bf16 v[60:63], v[68:71], v[92:95], v[60:63]
	ds_read_b128 v[120:123], v220 offset:61440
	s_waitcnt lgkmcnt(6)
	v_mfma_f32_16x16x32_bf16 v[0:3], v[72:75], v[96:99], v[0:3]
	v_mfma_f32_16x16x32_bf16 v[32:35], v[76:79], v[96:99], v[32:35]
	ds_read_b128 v[124:127], v220 offset:63488
	s_waitcnt vmcnt(0) lgkmcnt(0)
	s_barrier
	s_add_u32 m0, s1, 32768
	s_nop 0
	global_load_lds_dwordx4 v222, s[84:85]
	s_waitcnt lgkmcnt(6)
	v_mfma_f32_16x16x32_bf16 v[4:7], v[72:75], v[100:103], v[4:7]
	v_mfma_f32_16x16x32_bf16 v[36:39], v[76:79], v[100:103], v[36:39]
	ds_read_b128 v[64:67], v142 offset:0
	ds_read_b128 v[68:71], v142 offset:2048
	ds_read_b128 v[80:83], v218 offset:16384
	s_add_u32 m0, s1, 36864
	s_nop 0
	global_load_lds_dwordx4 v224, s[84:85]
	s_waitcnt lgkmcnt(8)
	v_mfma_f32_16x16x32_bf16 v[8:11], v[72:75], v[104:107], v[8:11]
	v_mfma_f32_16x16x32_bf16 v[40:43], v[76:79], v[104:107], v[40:43]
	ds_read_b128 v[84:87], v218 offset:18432
	s_add_u32 m0, s1, 40960
	s_nop 0
	global_load_lds_dwordx4 v226, s[84:85]
	s_waitcnt lgkmcnt(8)
	v_mfma_f32_16x16x32_bf16 v[12:15], v[72:75], v[108:111], v[12:15]
	v_mfma_f32_16x16x32_bf16 v[44:47], v[76:79], v[108:111], v[44:47]
	ds_read_b128 v[88:91], v218 offset:20480
	s_add_u32 m0, s1, 45056
	s_nop 0
	global_load_lds_dwordx4 v228, s[84:85]
	s_add_u32 s84, s84, 128
	s_addc_u32 s85, s85, 0
	s_waitcnt lgkmcnt(8)
	v_mfma_f32_16x16x32_bf16 v[16:19], v[72:75], v[112:115], v[16:19]
	v_mfma_f32_16x16x32_bf16 v[48:51], v[76:79], v[112:115], v[48:51]
	ds_read_b128 v[92:95], v218 offset:22528
	s_add_u32 m0, s1, 49152
	s_nop 0
	global_load_lds_dwordx4 v222, s[86:87]
	s_waitcnt lgkmcnt(8)
	v_mfma_f32_16x16x32_bf16 v[20:23], v[72:75], v[116:119], v[20:23]
	v_mfma_f32_16x16x32_bf16 v[52:55], v[76:79], v[116:119], v[52:55]
	ds_read_b128 v[96:99], v218 offset:24576
	s_add_u32 m0, s1, 53248
	s_nop 0
	global_load_lds_dwordx4 v224, s[86:87]
	s_waitcnt lgkmcnt(8)
	v_mfma_f32_16x16x32_bf16 v[24:27], v[72:75], v[120:123], v[24:27]
	v_mfma_f32_16x16x32_bf16 v[56:59], v[76:79], v[120:123], v[56:59]
	ds_read_b128 v[100:103], v218 offset:26624
	s_add_u32 m0, s1, 57344
	s_nop 0
	global_load_lds_dwordx4 v226, s[86:87]
	s_waitcnt lgkmcnt(8)
	v_mfma_f32_16x16x32_bf16 v[28:31], v[72:75], v[124:127], v[28:31]
	v_mfma_f32_16x16x32_bf16 v[60:63], v[76:79], v[124:127], v[60:63]
	ds_read_b128 v[104:107], v218 offset:28672
	s_add_u32 m0, s1, 61440
	s_nop 0
	global_load_lds_dwordx4 v228, s[86:87]
	s_add_u32 s86, s86, 128
	s_addc_u32 s87, s87, 0
	s_waitcnt lgkmcnt(6)
	v_mfma_f32_16x16x32_bf16 v[0:3], v[64:67], v[80:83], v[0:3]
	v_mfma_f32_16x16x32_bf16 v[32:35], v[68:71], v[80:83], v[32:35]
	ds_read_b128 v[108:111], v218 offset:30720
	s_waitcnt lgkmcnt(6)
	v_mfma_f32_16x16x32_bf16 v[4:7], v[64:67], v[84:87], v[4:7]
	v_mfma_f32_16x16x32_bf16 v[36:39], v[68:71], v[84:87], v[36:39]
	ds_read_b128 v[72:75], v216 offset:0
	ds_read_b128 v[76:79], v216 offset:2048
	ds_read_b128 v[112:115], v220 offset:16384
	s_waitcnt lgkmcnt(8)
	v_mfma_f32_16x16x32_bf16 v[8:11], v[64:67], v[88:91], v[8:11]
	v_mfma_f32_16x16x32_bf16 v[40:43], v[68:71], v[88:91], v[40:43]
	ds_read_b128 v[116:119], v220 offset:18432
	s_waitcnt lgkmcnt(8)
	v_mfma_f32_16x16x32_bf16 v[12:15], v[64:67], v[92:95], v[12:15]
	v_mfma_f32_16x16x32_bf16 v[44:47], v[68:71], v[92:95], v[44:47]
	ds_read_b128 v[120:123], v220 offset:20480
	s_waitcnt lgkmcnt(8)
	v_mfma_f32_16x16x32_bf16 v[16:19], v[64:67], v[96:99], v[16:19]
	v_mfma_f32_16x16x32_bf16 v[48:51], v[68:71], v[96:99], v[48:51]
	ds_read_b128 v[124:127], v220 offset:22528
	s_waitcnt lgkmcnt(8)
	v_mfma_f32_16x16x32_bf16 v[20:23], v[64:67], v[100:103], v[20:23]
	v_mfma_f32_16x16x32_bf16 v[52:55], v[68:71], v[100:103], v[52:55]
	ds_read_b128 v[80:83], v220 offset:24576
	s_waitcnt lgkmcnt(8)
	v_mfma_f32_16x16x32_bf16 v[24:27], v[64:67], v[104:107], v[24:27]
	v_mfma_f32_16x16x32_bf16 v[56:59], v[68:71], v[104:107], v[56:59]
	ds_read_b128 v[84:87], v220 offset:26624
	s_waitcnt lgkmcnt(8)
	v_mfma_f32_16x16x32_bf16 v[28:31], v[64:67], v[108:111], v[28:31]
	v_mfma_f32_16x16x32_bf16 v[60:63], v[68:71], v[108:111], v[60:63]
	ds_read_b128 v[88:91], v220 offset:28672
	s_waitcnt lgkmcnt(6)
	v_mfma_f32_16x16x32_bf16 v[0:3], v[72:75], v[112:115], v[0:3]
	v_mfma_f32_16x16x32_bf16 v[32:35], v[76:79], v[112:115], v[32:35]
	ds_read_b128 v[92:95], v220 offset:30720
	s_waitcnt vmcnt(0) lgkmcnt(0)
	s_barrier
	s_add_u32 m0, s1, 0
	s_nop 0
	global_load_lds_dwordx4 v222, s[84:85]
	s_waitcnt lgkmcnt(6)
	v_mfma_f32_16x16x32_bf16 v[4:7], v[72:75], v[116:119], v[4:7]
	v_mfma_f32_16x16x32_bf16 v[36:39], v[76:79], v[116:119], v[36:39]
	ds_read_b128 v[64:67], v142 offset:32768
	ds_read_b128 v[68:71], v142 offset:34816
	ds_read_b128 v[96:99], v218 offset:49152
	s_add_u32 m0, s1, 4096
	s_nop 0
	global_load_lds_dwordx4 v224, s[84:85]
	s_waitcnt lgkmcnt(8)
	v_mfma_f32_16x16x32_bf16 v[8:11], v[72:75], v[120:123], v[8:11]
	v_mfma_f32_16x16x32_bf16 v[40:43], v[76:79], v[120:123], v[40:43]
	ds_read_b128 v[100:103], v218 offset:51200
	s_add_u32 m0, s1, 8192
	s_nop 0
	global_load_lds_dwordx4 v226, s[84:85]
	s_waitcnt lgkmcnt(8)
	v_mfma_f32_16x16x32_bf16 v[12:15], v[72:75], v[124:127], v[12:15]
	v_mfma_f32_16x16x32_bf16 v[44:47], v[76:79], v[124:127], v[44:47]
	ds_read_b128 v[104:107], v218 offset:53248
	s_add_u32 m0, s1, 12288
	s_nop 0
	global_load_lds_dwordx4 v228, s[84:85]
	s_add_u32 s84, s84, 128
	s_addc_u32 s85, s85, 0
	s_waitcnt lgkmcnt(8)
	v_mfma_f32_16x16x32_bf16 v[16:19], v[72:75], v[80:83], v[16:19]
	v_mfma_f32_16x16x32_bf16 v[48:51], v[76:79], v[80:83], v[48:51]
	ds_read_b128 v[108:111], v218 offset:55296
	s_add_u32 m0, s1, 16384
	s_nop 0
	global_load_lds_dwordx4 v222, s[86:87]
	s_waitcnt lgkmcnt(8)
	v_mfma_f32_16x16x32_bf16 v[20:23], v[72:75], v[84:87], v[20:23]
	v_mfma_f32_16x16x32_bf16 v[52:55], v[76:79], v[84:87], v[52:55]
	ds_read_b128 v[112:115], v218 offset:57344
	s_add_u32 m0, s1, 20480
	s_nop 0
	global_load_lds_dwordx4 v224, s[86:87]
	s_waitcnt lgkmcnt(8)
	v_mfma_f32_16x16x32_bf16 v[24:27], v[72:75], v[88:91], v[24:27]
	v_mfma_f32_16x16x32_bf16 v[56:59], v[76:79], v[88:91], v[56:59]
	ds_read_b128 v[116:119], v218 offset:59392
	s_add_u32 m0, s1, 24576
	s_nop 0
	global_load_lds_dwordx4 v226, s[86:87]
	s_waitcnt lgkmcnt(8)
	v_mfma_f32_16x16x32_bf16 v[28:31], v[72:75], v[92:95], v[28:31]
	v_mfma_f32_16x16x32_bf16 v[60:63], v[76:79], v[92:95], v[60:63]
	ds_read_b128 v[120:123], v218 offset:61440
	s_add_u32 m0, s1, 28672
	s_nop 0
	global_load_lds_dwordx4 v228, s[86:87]
	s_add_u32 s86, s86, 128
	s_addc_u32 s87, s87, 0
	s_waitcnt lgkmcnt(6)
	v_mfma_f32_16x16x32_bf16 v[0:3], v[64:67], v[96:99], v[0:3]
	v_mfma_f32_16x16x32_bf16 v[32:35], v[68:71], v[96:99], v[32:35]
	ds_read_b128 v[124:127], v218 offset:63488
	s_waitcnt lgkmcnt(6)
	v_mfma_f32_16x16x32_bf16 v[4:7], v[64:67], v[100:103], v[4:7]
	v_mfma_f32_16x16x32_bf16 v[36:39], v[68:71], v[100:103], v[36:39]
	ds_read_b128 v[72:75], v216 offset:32768
	ds_read_b128 v[76:79], v216 offset:34816
	ds_read_b128 v[80:83], v220 offset:49152
	s_waitcnt lgkmcnt(8)
	v_mfma_f32_16x16x32_bf16 v[8:11], v[64:67], v[104:107], v[8:11]
	v_mfma_f32_16x16x32_bf16 v[40:43], v[68:71], v[104:107], v[40:43]
	ds_read_b128 v[84:87], v220 offset:51200
	s_waitcnt lgkmcnt(8)
	v_mfma_f32_16x16x32_bf16 v[12:15], v[64:67], v[108:111], v[12:15]
	v_mfma_f32_16x16x32_bf16 v[44:47], v[68:71], v[108:111], v[44:47]
	ds_read_b128 v[88:91], v220 offset:53248
	s_waitcnt lgkmcnt(8)
	v_mfma_f32_16x16x32_bf16 v[16:19], v[64:67], v[112:115], v[16:19]
	v_mfma_f32_16x16x32_bf16 v[48:51], v[68:71], v[112:115], v[48:51]
	ds_read_b128 v[92:95], v220 offset:55296
	s_waitcnt lgkmcnt(8)
	v_mfma_f32_16x16x32_bf16 v[20:23], v[64:67], v[116:119], v[20:23]
	v_mfma_f32_16x16x32_bf16 v[52:55], v[68:71], v[116:119], v[52:55]
	ds_read_b128 v[96:99], v220 offset:57344
	s_waitcnt lgkmcnt(8)
	v_mfma_f32_16x16x32_bf16 v[24:27], v[64:67], v[120:123], v[24:27]
	v_mfma_f32_16x16x32_bf16 v[56:59], v[68:71], v[120:123], v[56:59]
	ds_read_b128 v[100:103], v220 offset:59392
	s_waitcnt lgkmcnt(8)
	v_mfma_f32_16x16x32_bf16 v[28:31], v[64:67], v[124:127], v[28:31]
	v_mfma_f32_16x16x32_bf16 v[60:63], v[68:71], v[124:127], v[60:63]
	ds_read_b128 v[104:107], v220 offset:61440
	s_waitcnt lgkmcnt(6)
	v_mfma_f32_16x16x32_bf16 v[0:3], v[72:75], v[80:83], v[0:3]
	v_mfma_f32_16x16x32_bf16 v[32:35], v[76:79], v[80:83], v[32:35]
	ds_read_b128 v[108:111], v220 offset:63488
	s_waitcnt vmcnt(0) lgkmcnt(0)
	s_barrier
	s_add_u32 m0, s1, 32768
	s_nop 0
	global_load_lds_dwordx4 v222, s[84:85]
	s_waitcnt lgkmcnt(6)
	v_mfma_f32_16x16x32_bf16 v[4:7], v[72:75], v[84:87], v[4:7]
	v_mfma_f32_16x16x32_bf16 v[36:39], v[76:79], v[84:87], v[36:39]
	ds_read_b128 v[64:67], v142 offset:0
	ds_read_b128 v[68:71], v142 offset:2048
	ds_read_b128 v[112:115], v218 offset:16384
	s_add_u32 m0, s1, 36864
	s_nop 0
	global_load_lds_dwordx4 v224, s[84:85]
	s_waitcnt lgkmcnt(8)
	v_mfma_f32_16x16x32_bf16 v[8:11], v[72:75], v[88:91], v[8:11]
	v_mfma_f32_16x16x32_bf16 v[40:43], v[76:79], v[88:91], v[40:43]
	ds_read_b128 v[116:119], v218 offset:18432
	s_add_u32 m0, s1, 40960
	s_nop 0
	global_load_lds_dwordx4 v226, s[84:85]
	s_waitcnt lgkmcnt(8)
	v_mfma_f32_16x16x32_bf16 v[12:15], v[72:75], v[92:95], v[12:15]
	v_mfma_f32_16x16x32_bf16 v[44:47], v[76:79], v[92:95], v[44:47]
	ds_read_b128 v[120:123], v218 offset:20480
	s_add_u32 m0, s1, 45056
	s_nop 0
	global_load_lds_dwordx4 v228, s[84:85]
	s_add_u32 s84, s84, 128
	s_addc_u32 s85, s85, 0
	s_waitcnt lgkmcnt(8)
	v_mfma_f32_16x16x32_bf16 v[16:19], v[72:75], v[96:99], v[16:19]
	v_mfma_f32_16x16x32_bf16 v[48:51], v[76:79], v[96:99], v[48:51]
	ds_read_b128 v[124:127], v218 offset:22528
	s_add_u32 m0, s1, 49152
	s_nop 0
	global_load_lds_dwordx4 v222, s[86:87]
	s_waitcnt lgkmcnt(8)
	v_mfma_f32_16x16x32_bf16 v[20:23], v[72:75], v[100:103], v[20:23]
	v_mfma_f32_16x16x32_bf16 v[52:55], v[76:79], v[100:103], v[52:55]
	ds_read_b128 v[80:83], v218 offset:24576
	s_add_u32 m0, s1, 53248
	s_nop 0
	global_load_lds_dwordx4 v224, s[86:87]
	s_waitcnt lgkmcnt(8)
	v_mfma_f32_16x16x32_bf16 v[24:27], v[72:75], v[104:107], v[24:27]
	v_mfma_f32_16x16x32_bf16 v[56:59], v[76:79], v[104:107], v[56:59]
	ds_read_b128 v[84:87], v218 offset:26624
	s_add_u32 m0, s1, 57344
	s_nop 0
	global_load_lds_dwordx4 v226, s[86:87]
	s_waitcnt lgkmcnt(8)
	v_mfma_f32_16x16x32_bf16 v[28:31], v[72:75], v[108:111], v[28:31]
	v_mfma_f32_16x16x32_bf16 v[60:63], v[76:79], v[108:111], v[60:63]
	ds_read_b128 v[88:91], v218 offset:28672
	s_add_u32 m0, s1, 61440
	s_nop 0
	global_load_lds_dwordx4 v228, s[86:87]
	s_add_u32 s86, s86, 128
	s_addc_u32 s87, s87, 0
	s_waitcnt lgkmcnt(6)
	v_mfma_f32_16x16x32_bf16 v[0:3], v[64:67], v[112:115], v[0:3]
	v_mfma_f32_16x16x32_bf16 v[32:35], v[68:71], v[112:115], v[32:35]
	ds_read_b128 v[92:95], v218 offset:30720
	s_waitcnt lgkmcnt(6)
	v_mfma_f32_16x16x32_bf16 v[4:7], v[64:67], v[116:119], v[4:7]
	v_mfma_f32_16x16x32_bf16 v[36:39], v[68:71], v[116:119], v[36:39]
	ds_read_b128 v[72:75], v216 offset:0
	ds_read_b128 v[76:79], v216 offset:2048
	ds_read_b128 v[96:99], v220 offset:16384
	s_waitcnt lgkmcnt(8)
	v_mfma_f32_16x16x32_bf16 v[8:11], v[64:67], v[120:123], v[8:11]
	v_mfma_f32_16x16x32_bf16 v[40:43], v[68:71], v[120:123], v[40:43]
	ds_read_b128 v[100:103], v220 offset:18432
	s_waitcnt lgkmcnt(8)
	v_mfma_f32_16x16x32_bf16 v[12:15], v[64:67], v[124:127], v[12:15]
	v_mfma_f32_16x16x32_bf16 v[44:47], v[68:71], v[124:127], v[44:47]
	ds_read_b128 v[104:107], v220 offset:20480
	s_waitcnt lgkmcnt(8)
	v_mfma_f32_16x16x32_bf16 v[16:19], v[64:67], v[80:83], v[16:19]
	v_mfma_f32_16x16x32_bf16 v[48:51], v[68:71], v[80:83], v[48:51]
	ds_read_b128 v[108:111], v220 offset:22528
	s_waitcnt lgkmcnt(8)
	v_mfma_f32_16x16x32_bf16 v[20:23], v[64:67], v[84:87], v[20:23]
	v_mfma_f32_16x16x32_bf16 v[52:55], v[68:71], v[84:87], v[52:55]
	ds_read_b128 v[112:115], v220 offset:24576
	s_waitcnt lgkmcnt(8)
	v_mfma_f32_16x16x32_bf16 v[24:27], v[64:67], v[88:91], v[24:27]
	v_mfma_f32_16x16x32_bf16 v[56:59], v[68:71], v[88:91], v[56:59]
	ds_read_b128 v[116:119], v220 offset:26624
	s_waitcnt lgkmcnt(8)
	v_mfma_f32_16x16x32_bf16 v[28:31], v[64:67], v[92:95], v[28:31]
	v_mfma_f32_16x16x32_bf16 v[60:63], v[68:71], v[92:95], v[60:63]
	ds_read_b128 v[120:123], v220 offset:28672
	s_waitcnt lgkmcnt(6)
	v_mfma_f32_16x16x32_bf16 v[0:3], v[72:75], v[96:99], v[0:3]
	v_mfma_f32_16x16x32_bf16 v[32:35], v[76:79], v[96:99], v[32:35]
	ds_read_b128 v[124:127], v220 offset:30720
	s_waitcnt vmcnt(0) lgkmcnt(0)
	s_barrier
	s_waitcnt lgkmcnt(6)
	v_mfma_f32_16x16x32_bf16 v[4:7], v[72:75], v[100:103], v[4:7]
	v_mfma_f32_16x16x32_bf16 v[36:39], v[76:79], v[100:103], v[36:39]
	ds_read_b128 v[64:67], v142 offset:32768
	ds_read_b128 v[68:71], v142 offset:34816
	ds_read_b128 v[80:83], v218 offset:49152
	s_waitcnt lgkmcnt(8)
	v_mfma_f32_16x16x32_bf16 v[8:11], v[72:75], v[104:107], v[8:11]
	v_mfma_f32_16x16x32_bf16 v[40:43], v[76:79], v[104:107], v[40:43]
	ds_read_b128 v[84:87], v218 offset:51200
	s_waitcnt lgkmcnt(8)
	v_mfma_f32_16x16x32_bf16 v[12:15], v[72:75], v[108:111], v[12:15]
	v_mfma_f32_16x16x32_bf16 v[44:47], v[76:79], v[108:111], v[44:47]
	ds_read_b128 v[88:91], v218 offset:53248
	s_waitcnt lgkmcnt(8)
	v_mfma_f32_16x16x32_bf16 v[16:19], v[72:75], v[112:115], v[16:19]
	v_mfma_f32_16x16x32_bf16 v[48:51], v[76:79], v[112:115], v[48:51]
	ds_read_b128 v[92:95], v218 offset:55296
	s_waitcnt lgkmcnt(8)
	v_mfma_f32_16x16x32_bf16 v[20:23], v[72:75], v[116:119], v[20:23]
	v_mfma_f32_16x16x32_bf16 v[52:55], v[76:79], v[116:119], v[52:55]
	ds_read_b128 v[96:99], v218 offset:57344
	s_waitcnt lgkmcnt(8)
	v_mfma_f32_16x16x32_bf16 v[24:27], v[72:75], v[120:123], v[24:27]
	v_mfma_f32_16x16x32_bf16 v[56:59], v[76:79], v[120:123], v[56:59]
	ds_read_b128 v[100:103], v218 offset:59392
	s_waitcnt lgkmcnt(8)
	v_mfma_f32_16x16x32_bf16 v[28:31], v[72:75], v[124:127], v[28:31]
	v_mfma_f32_16x16x32_bf16 v[60:63], v[76:79], v[124:127], v[60:63]
	ds_read_b128 v[104:107], v218 offset:61440
	s_waitcnt lgkmcnt(6)
	v_mfma_f32_16x16x32_bf16 v[0:3], v[64:67], v[80:83], v[0:3]
	v_mfma_f32_16x16x32_bf16 v[32:35], v[68:71], v[80:83], v[32:35]
	ds_read_b128 v[108:111], v218 offset:63488
	s_waitcnt lgkmcnt(6)
	v_mfma_f32_16x16x32_bf16 v[4:7], v[64:67], v[84:87], v[4:7]
	v_mfma_f32_16x16x32_bf16 v[36:39], v[68:71], v[84:87], v[36:39]
	ds_read_b128 v[72:75], v216 offset:32768
	ds_read_b128 v[76:79], v216 offset:34816
	ds_read_b128 v[112:115], v220 offset:49152
	s_waitcnt lgkmcnt(8)
	v_mfma_f32_16x16x32_bf16 v[8:11], v[64:67], v[88:91], v[8:11]
	v_mfma_f32_16x16x32_bf16 v[40:43], v[68:71], v[88:91], v[40:43]
	ds_read_b128 v[116:119], v220 offset:51200
	s_waitcnt lgkmcnt(8)
	v_mfma_f32_16x16x32_bf16 v[12:15], v[64:67], v[92:95], v[12:15]
	v_mfma_f32_16x16x32_bf16 v[44:47], v[68:71], v[92:95], v[44:47]
	ds_read_b128 v[120:123], v220 offset:53248
	s_waitcnt lgkmcnt(8)
	v_mfma_f32_16x16x32_bf16 v[16:19], v[64:67], v[96:99], v[16:19]
	v_mfma_f32_16x16x32_bf16 v[48:51], v[68:71], v[96:99], v[48:51]
	ds_read_b128 v[124:127], v220 offset:55296
	s_waitcnt lgkmcnt(8)
	v_mfma_f32_16x16x32_bf16 v[20:23], v[64:67], v[100:103], v[20:23]
	v_mfma_f32_16x16x32_bf16 v[52:55], v[68:71], v[100:103], v[52:55]
	ds_read_b128 v[80:83], v220 offset:57344
	s_waitcnt lgkmcnt(8)
	v_mfma_f32_16x16x32_bf16 v[24:27], v[64:67], v[104:107], v[24:27]
	v_mfma_f32_16x16x32_bf16 v[56:59], v[68:71], v[104:107], v[56:59]
	ds_read_b128 v[84:87], v220 offset:59392
	s_waitcnt lgkmcnt(8)
	v_mfma_f32_16x16x32_bf16 v[28:31], v[64:67], v[108:111], v[28:31]
	v_mfma_f32_16x16x32_bf16 v[60:63], v[68:71], v[108:111], v[60:63]
	ds_read_b128 v[88:91], v220 offset:61440
	s_waitcnt lgkmcnt(6)
	v_mfma_f32_16x16x32_bf16 v[0:3], v[72:75], v[112:115], v[0:3]
	v_mfma_f32_16x16x32_bf16 v[32:35], v[76:79], v[112:115], v[32:35]
	ds_read_b128 v[92:95], v220 offset:63488
	s_waitcnt lgkmcnt(6)
	v_mfma_f32_16x16x32_bf16 v[4:7], v[72:75], v[116:119], v[4:7]
	v_mfma_f32_16x16x32_bf16 v[36:39], v[76:79], v[116:119], v[36:39]
	s_waitcnt lgkmcnt(5)
	v_mfma_f32_16x16x32_bf16 v[8:11], v[72:75], v[120:123], v[8:11]
	v_mfma_f32_16x16x32_bf16 v[40:43], v[76:79], v[120:123], v[40:43]
	s_waitcnt lgkmcnt(4)
	v_mfma_f32_16x16x32_bf16 v[12:15], v[72:75], v[124:127], v[12:15]
	v_mfma_f32_16x16x32_bf16 v[44:47], v[76:79], v[124:127], v[44:47]
	s_waitcnt lgkmcnt(3)
	v_mfma_f32_16x16x32_bf16 v[16:19], v[72:75], v[80:83], v[16:19]
	v_mfma_f32_16x16x32_bf16 v[48:51], v[76:79], v[80:83], v[48:51]
	s_waitcnt lgkmcnt(2)
	v_mfma_f32_16x16x32_bf16 v[20:23], v[72:75], v[84:87], v[20:23]
	v_mfma_f32_16x16x32_bf16 v[52:55], v[76:79], v[84:87], v[52:55]
	s_waitcnt lgkmcnt(1)
	v_mfma_f32_16x16x32_bf16 v[24:27], v[72:75], v[88:91], v[24:27]
	v_mfma_f32_16x16x32_bf16 v[56:59], v[76:79], v[88:91], v[56:59]
	s_waitcnt lgkmcnt(0)
	v_mfma_f32_16x16x32_bf16 v[28:31], v[72:75], v[92:95], v[28:31]
	v_mfma_f32_16x16x32_bf16 v[60:63], v[76:79], v[92:95], v[60:63]
	s_nop 7
	s_nop 7
	s_waitcnt vmcnt(0) lgkmcnt(0)
	s_barrier
	s_mov_b64 s[6:7], -1
	s_cmp_lt_i32 s77, 5
	s_cbranch_scc1 .LBB0_175
	v_mul_f32_e32 v64, 0xbfb8aa3b, v2
	v_mul_f32_e32 v65, 0xbfb8aa3b, v3
	v_exp_f32_e32 v64, v64
	v_exp_f32_e32 v65, v65
	v_mul_f32_e32 v66, 0xbfb8aa3b, v0
	v_mul_f32_e32 v67, 0xbfb8aa3b, v1
	v_exp_f32_e32 v66, v66
	v_pk_add_f32 v[64:65], v[64:65], 1.0 op_sel_hi:[1,0]
	v_exp_f32_e32 v67, v67
	v_div_scale_f32 v70, s[4:5], v65, v65, v3
	v_rcp_f32_e32 v71, v70
	v_pk_add_f32 v[68:69], v[66:67], 1.0 op_sel_hi:[1,0]
	v_mul_f32_e32 v73, 0xbfb8aa3b, v5
	v_exp_f32_e32 v73, v73
	v_fma_f32 v66, -v70, v71, 1.0
	v_fmac_f32_e32 v71, v66, v71
	v_div_scale_f32 v66, vcc, v3, v65, v3
	v_mul_f32_e32 v67, v66, v71
	v_fma_f32 v72, -v70, v67, v66
	v_fmac_f32_e32 v67, v72, v71
	v_fma_f32 v66, -v70, v67, v66
	v_div_scale_f32 v70, s[4:5], v64, v64, v2
	v_rcp_f32_e32 v72, v70
	v_div_fmas_f32 v66, v66, v71, v67
	v_div_fixup_f32 v67, v66, v65, v3
	v_mul_f32_e32 v81, 0xbfb8aa3b, v13
	v_fma_f32 v65, -v70, v72, 1.0
	v_fmac_f32_e32 v72, v65, v72
	v_div_scale_f32 v65, vcc, v2, v64, v2
	v_mul_f32_e32 v66, v65, v72
	v_fma_f32 v71, -v70, v66, v65
	v_fmac_f32_e32 v66, v71, v72
	v_fma_f32 v65, -v70, v66, v65
	v_div_scale_f32 v70, s[4:5], v69, v69, v1
	v_rcp_f32_e32 v71, v70
	v_div_fmas_f32 v65, v65, v72, v66
	v_div_fixup_f32 v66, v65, v64, v2
	v_exp_f32_e32 v81, v81
	v_fma_f32 v64, -v70, v71, 1.0
	v_fmac_f32_e32 v71, v64, v71
	v_div_scale_f32 v64, vcc, v1, v69, v1
	v_mul_f32_e32 v65, v64, v71
	v_fma_f32 v72, -v70, v65, v64
	v_fmac_f32_e32 v65, v72, v71
	v_fma_f32 v64, -v70, v65, v64
	v_div_scale_f32 v70, s[4:5], v68, v68, v0
	v_rcp_f32_e32 v74, v70
	v_div_fmas_f32 v64, v64, v71, v65
	v_div_fixup_f32 v65, v64, v69, v1
	v_mul_f32_e32 v72, 0xbfb8aa3b, v4
	v_fma_f32 v64, -v70, v74, 1.0
	v_fmac_f32_e32 v74, v64, v74
	v_div_scale_f32 v64, vcc, v0, v68, v0
	v_mul_f32_e32 v69, v64, v74
	v_fma_f32 v71, -v70, v69, v64
	v_fmac_f32_e32 v69, v71, v74
	v_fma_f32 v64, -v70, v69, v64
	v_mul_f32_e32 v70, 0xbfb8aa3b, v6
	v_mul_f32_e32 v71, 0xbfb8aa3b, v7
	v_exp_f32_e32 v70, v70
	v_exp_f32_e32 v71, v71
	v_exp_f32_e32 v72, v72
	v_div_fmas_f32 v64, v64, v74, v69
	v_div_fixup_f32 v64, v64, v68, v0
	v_pk_add_f32 v[70:71], v[70:71], 1.0 op_sel_hi:[1,0]
	v_pk_add_f32 v[68:69], v[72:73], 1.0 op_sel_hi:[1,0]
	v_div_scale_f32 v75, s[4:5], v71, v71, v7
	v_rcp_f32_e32 v76, v75
	v_mul_f32_e32 v89, 0xbfb8aa3b, v21
	v_exp_f32_e32 v89, v89
	v_mul_f32_e32 v97, 0xbfb8aa3b, v29
	v_fma_f32 v72, -v75, v76, 1.0
	v_fmac_f32_e32 v76, v72, v76
	v_div_scale_f32 v72, vcc, v7, v71, v7
	v_mul_f32_e32 v73, v72, v76
	v_fma_f32 v74, -v75, v73, v72
	v_fmac_f32_e32 v73, v74, v76
	v_div_scale_f32 v74, s[4:5], v70, v70, v6
	v_fma_f32 v72, -v75, v73, v72
	v_rcp_f32_e32 v75, v74
	v_div_fmas_f32 v72, v72, v76, v73
	v_div_fixup_f32 v71, v72, v71, v7
	v_exp_f32_e32 v97, v97
	v_fma_f32 v72, -v74, v75, 1.0
	v_fmac_f32_e32 v75, v72, v75
	v_div_scale_f32 v72, vcc, v6, v70, v6
	v_mul_f32_e32 v73, v72, v75
	v_fma_f32 v76, -v74, v73, v72
	v_fmac_f32_e32 v73, v76, v75
	v_fma_f32 v72, -v74, v73, v72
	v_div_scale_f32 v74, s[4:5], v69, v69, v5
	v_rcp_f32_e32 v76, v74
	v_div_fmas_f32 v72, v72, v75, v73
	v_div_fixup_f32 v70, v72, v70, v6
	v_mul_f32_e32 v105, 0xbfb8aa3b, v37
	v_fma_f32 v72, -v74, v76, 1.0
	v_fmac_f32_e32 v76, v72, v76
	v_div_scale_f32 v72, vcc, v5, v69, v5
	v_mul_f32_e32 v73, v72, v76
	v_fma_f32 v75, -v74, v73, v72
	v_fmac_f32_e32 v73, v75, v76
	v_fma_f32 v72, -v74, v73, v72
	v_div_scale_f32 v74, s[4:5], v68, v68, v4
	v_rcp_f32_e32 v77, v74
	v_div_fmas_f32 v72, v72, v76, v73
	v_div_fixup_f32 v69, v72, v69, v5
	v_mul_f32_e32 v75, 0xbfb8aa3b, v9
	v_fma_f32 v72, -v74, v77, 1.0
	v_fmac_f32_e32 v77, v72, v77
	v_div_scale_f32 v72, vcc, v4, v68, v4
	v_mul_f32_e32 v76, v72, v77
	v_fma_f32 v73, -v74, v76, v72
	v_fmac_f32_e32 v76, v73, v77
	v_fma_f32 v78, -v74, v76, v72
	v_mul_f32_e32 v72, 0xbfb8aa3b, v10
	v_mul_f32_e32 v73, 0xbfb8aa3b, v11
	v_exp_f32_e32 v72, v72
	v_exp_f32_e32 v73, v73
	v_mul_f32_e32 v74, 0xbfb8aa3b, v8
	v_exp_f32_e32 v74, v74
	v_exp_f32_e32 v75, v75
	v_pk_add_f32 v[72:73], v[72:73], 1.0 op_sel_hi:[1,0]
	v_div_fmas_f32 v76, v78, v77, v76
	v_div_scale_f32 v79, s[4:5], v73, v73, v11
	v_rcp_f32_e32 v80, v79
	v_div_fixup_f32 v68, v76, v68, v4
	v_pk_add_f32 v[76:77], v[74:75], 1.0 op_sel_hi:[1,0]
	v_exp_f32_e32 v105, v105
	v_fma_f32 v74, -v79, v80, 1.0
	v_fmac_f32_e32 v80, v74, v80
	v_div_scale_f32 v74, vcc, v11, v73, v11
	v_mul_f32_e32 v75, v74, v80
	v_fma_f32 v78, -v79, v75, v74
	v_fmac_f32_e32 v75, v78, v80
	v_div_scale_f32 v78, s[4:5], v72, v72, v10
	v_fma_f32 v74, -v79, v75, v74
	v_rcp_f32_e32 v79, v78
	v_div_fmas_f32 v74, v74, v80, v75
	v_div_fixup_f32 v75, v74, v73, v11
	v_mul_f32_e32 v113, 0xbfb8aa3b, v45
	v_fma_f32 v73, -v78, v79, 1.0
	v_fmac_f32_e32 v79, v73, v79
	v_div_scale_f32 v73, vcc, v10, v72, v10
	v_mul_f32_e32 v74, v73, v79
	v_fma_f32 v80, -v78, v74, v73
	v_fmac_f32_e32 v74, v80, v79
	v_fma_f32 v73, -v78, v74, v73
	v_div_scale_f32 v78, s[4:5], v77, v77, v9
	v_rcp_f32_e32 v80, v78
	v_div_fmas_f32 v73, v73, v79, v74
	v_div_fixup_f32 v74, v73, v72, v10
	v_exp_f32_e32 v113, v113
	v_fma_f32 v72, -v78, v80, 1.0
	v_fmac_f32_e32 v80, v72, v80
	v_div_scale_f32 v72, vcc, v9, v77, v9
	v_mul_f32_e32 v73, v72, v80
	v_fma_f32 v79, -v78, v73, v72
	v_fmac_f32_e32 v73, v79, v80
	v_fma_f32 v72, -v78, v73, v72
	v_div_scale_f32 v78, s[4:5], v76, v76, v8
	v_rcp_f32_e32 v82, v78
	v_div_fmas_f32 v72, v72, v80, v73
	v_div_fixup_f32 v73, v72, v77, v9
	v_mul_f32_e32 v80, 0xbfb8aa3b, v12
	v_fma_f32 v72, -v78, v82, 1.0
	v_fmac_f32_e32 v82, v72, v82
	v_div_scale_f32 v72, vcc, v8, v76, v8
	v_mul_f32_e32 v77, v72, v82
	v_fma_f32 v79, -v78, v77, v72
	v_fmac_f32_e32 v77, v79, v82
	v_fma_f32 v72, -v78, v77, v72
	v_mul_f32_e32 v78, 0xbfb8aa3b, v14
	v_mul_f32_e32 v79, 0xbfb8aa3b, v15
	v_exp_f32_e32 v78, v78
	v_exp_f32_e32 v79, v79
	v_exp_f32_e32 v80, v80
	v_div_fmas_f32 v72, v72, v82, v77
	v_div_fixup_f32 v72, v72, v76, v8
	v_pk_add_f32 v[78:79], v[78:79], 1.0 op_sel_hi:[1,0]
	v_pk_add_f32 v[76:77], v[80:81], 1.0 op_sel_hi:[1,0]
	v_div_scale_f32 v83, s[4:5], v79, v79, v15
	v_rcp_f32_e32 v84, v83
	v_mul_f32_e32 v121, 0xbfb8aa3b, v53
	v_exp_f32_e32 v121, v121
	s_mov_b64 s[6:7], 0
	v_fma_f32 v80, -v83, v84, 1.0
	v_fmac_f32_e32 v84, v80, v84
	v_div_scale_f32 v80, vcc, v15, v79, v15
	v_mul_f32_e32 v81, v80, v84
	v_fma_f32 v82, -v83, v81, v80
	v_fmac_f32_e32 v81, v82, v84
	v_div_scale_f32 v82, s[4:5], v78, v78, v14
	v_fma_f32 v80, -v83, v81, v80
	v_rcp_f32_e32 v83, v82
	v_div_fmas_f32 v80, v80, v84, v81
	v_div_fixup_f32 v79, v80, v79, v15
	v_fma_f32 v80, -v82, v83, 1.0
	v_fmac_f32_e32 v83, v80, v83
	v_div_scale_f32 v80, vcc, v14, v78, v14
	v_mul_f32_e32 v81, v80, v83
	v_fma_f32 v84, -v82, v81, v80
	v_fmac_f32_e32 v81, v84, v83
	v_fma_f32 v80, -v82, v81, v80
	v_div_scale_f32 v82, s[4:5], v77, v77, v13
	v_rcp_f32_e32 v84, v82
	v_div_fmas_f32 v80, v80, v83, v81
	v_div_fixup_f32 v78, v80, v78, v14
	v_fma_f32 v80, -v82, v84, 1.0
	v_fmac_f32_e32 v84, v80, v84
	v_div_scale_f32 v80, vcc, v13, v77, v13
	v_mul_f32_e32 v81, v80, v84
	v_fma_f32 v83, -v82, v81, v80
	v_fmac_f32_e32 v81, v83, v84
	v_fma_f32 v80, -v82, v81, v80
	v_div_scale_f32 v82, s[4:5], v76, v76, v12
	v_rcp_f32_e32 v85, v82
	v_div_fmas_f32 v80, v80, v84, v81
	v_div_fixup_f32 v77, v80, v77, v13
	v_mul_f32_e32 v83, 0xbfb8aa3b, v17
	v_fma_f32 v80, -v82, v85, 1.0
	v_fmac_f32_e32 v85, v80, v85
	v_div_scale_f32 v80, vcc, v12, v76, v12
	v_mul_f32_e32 v84, v80, v85
	v_fma_f32 v81, -v82, v84, v80
	v_fmac_f32_e32 v84, v81, v85
	v_fma_f32 v86, -v82, v84, v80
	v_mul_f32_e32 v80, 0xbfb8aa3b, v18
	v_mul_f32_e32 v81, 0xbfb8aa3b, v19
	v_exp_f32_e32 v80, v80
	v_exp_f32_e32 v81, v81
	v_mul_f32_e32 v82, 0xbfb8aa3b, v16
	v_exp_f32_e32 v82, v82
	v_exp_f32_e32 v83, v83
	v_pk_add_f32 v[80:81], v[80:81], 1.0 op_sel_hi:[1,0]
	v_div_fmas_f32 v84, v86, v85, v84
	v_div_scale_f32 v87, s[4:5], v81, v81, v19
	v_rcp_f32_e32 v88, v87
	v_div_fixup_f32 v76, v84, v76, v12
	v_pk_add_f32 v[84:85], v[82:83], 1.0 op_sel_hi:[1,0]
	v_fma_f32 v82, -v87, v88, 1.0
	v_fmac_f32_e32 v88, v82, v88
	v_div_scale_f32 v82, vcc, v19, v81, v19
	v_mul_f32_e32 v83, v82, v88
	v_fma_f32 v86, -v87, v83, v82
	v_fmac_f32_e32 v83, v86, v88
	v_div_scale_f32 v86, s[4:5], v80, v80, v18
	v_fma_f32 v82, -v87, v83, v82
	v_rcp_f32_e32 v87, v86
	v_div_fmas_f32 v82, v82, v88, v83
	v_div_fixup_f32 v83, v82, v81, v19
	v_fma_f32 v81, -v86, v87, 1.0
	v_fmac_f32_e32 v87, v81, v87
	v_div_scale_f32 v81, vcc, v18, v80, v18
	v_mul_f32_e32 v82, v81, v87
	v_fma_f32 v88, -v86, v82, v81
	v_fmac_f32_e32 v82, v88, v87
	v_fma_f32 v81, -v86, v82, v81
	v_div_scale_f32 v86, s[4:5], v85, v85, v17
	v_rcp_f32_e32 v88, v86
	v_div_fmas_f32 v81, v81, v87, v82
	v_div_fixup_f32 v82, v81, v80, v18
	v_fma_f32 v80, -v86, v88, 1.0
	v_fmac_f32_e32 v88, v80, v88
	v_div_scale_f32 v80, vcc, v17, v85, v17
	v_mul_f32_e32 v81, v80, v88
	v_fma_f32 v87, -v86, v81, v80
	v_fmac_f32_e32 v81, v87, v88
	v_fma_f32 v80, -v86, v81, v80
	v_div_scale_f32 v86, s[4:5], v84, v84, v16
	v_rcp_f32_e32 v90, v86
	v_div_fmas_f32 v80, v80, v88, v81
	v_div_fixup_f32 v81, v80, v85, v17
	v_mul_f32_e32 v88, 0xbfb8aa3b, v20
	v_fma_f32 v80, -v86, v90, 1.0
	v_fmac_f32_e32 v90, v80, v90
	v_div_scale_f32 v80, vcc, v16, v84, v16
	v_mul_f32_e32 v85, v80, v90
	v_fma_f32 v87, -v86, v85, v80
	v_fmac_f32_e32 v85, v87, v90
	v_fma_f32 v80, -v86, v85, v80
	v_mul_f32_e32 v86, 0xbfb8aa3b, v22
	v_mul_f32_e32 v87, 0xbfb8aa3b, v23
	v_exp_f32_e32 v86, v86
	v_exp_f32_e32 v87, v87
	v_exp_f32_e32 v88, v88
	v_div_fmas_f32 v80, v80, v90, v85
	v_div_fixup_f32 v80, v80, v84, v16
	v_pk_add_f32 v[86:87], v[86:87], 1.0 op_sel_hi:[1,0]
	v_pk_add_f32 v[84:85], v[88:89], 1.0 op_sel_hi:[1,0]
	v_div_scale_f32 v91, s[4:5], v87, v87, v23
	v_rcp_f32_e32 v92, v91
	s_nop 0
	v_fma_f32 v88, -v91, v92, 1.0
	v_fmac_f32_e32 v92, v88, v92
	v_div_scale_f32 v88, vcc, v23, v87, v23
	v_mul_f32_e32 v89, v88, v92
	v_fma_f32 v90, -v91, v89, v88
	v_fmac_f32_e32 v89, v90, v92
	v_div_scale_f32 v90, s[4:5], v86, v86, v22
	v_fma_f32 v88, -v91, v89, v88
	v_rcp_f32_e32 v91, v90
	v_div_fmas_f32 v88, v88, v92, v89
	v_div_fixup_f32 v87, v88, v87, v23
	v_fma_f32 v88, -v90, v91, 1.0
	v_fmac_f32_e32 v91, v88, v91
	v_div_scale_f32 v88, vcc, v22, v86, v22
	v_mul_f32_e32 v89, v88, v91
	v_fma_f32 v92, -v90, v89, v88
	v_fmac_f32_e32 v89, v92, v91
	v_fma_f32 v88, -v90, v89, v88
	v_div_scale_f32 v90, s[4:5], v85, v85, v21
	v_rcp_f32_e32 v92, v90
	v_div_fmas_f32 v88, v88, v91, v89
	v_div_fixup_f32 v86, v88, v86, v22
	v_fma_f32 v88, -v90, v92, 1.0
	v_fmac_f32_e32 v92, v88, v92
	v_div_scale_f32 v88, vcc, v21, v85, v21
	v_mul_f32_e32 v89, v88, v92
	v_fma_f32 v91, -v90, v89, v88
	v_fmac_f32_e32 v89, v91, v92
	v_fma_f32 v88, -v90, v89, v88
	v_div_scale_f32 v90, s[4:5], v84, v84, v20
	v_rcp_f32_e32 v93, v90
	v_div_fmas_f32 v88, v88, v92, v89
	v_div_fixup_f32 v85, v88, v85, v21
	v_mul_f32_e32 v91, 0xbfb8aa3b, v25
	v_fma_f32 v88, -v90, v93, 1.0
	v_fmac_f32_e32 v93, v88, v93
	v_div_scale_f32 v88, vcc, v20, v84, v20
	v_mul_f32_e32 v92, v88, v93
	v_fma_f32 v89, -v90, v92, v88
	v_fmac_f32_e32 v92, v89, v93
	v_fma_f32 v94, -v90, v92, v88
	v_mul_f32_e32 v88, 0xbfb8aa3b, v26
	v_mul_f32_e32 v89, 0xbfb8aa3b, v27
	v_exp_f32_e32 v88, v88
	v_exp_f32_e32 v89, v89
	v_mul_f32_e32 v90, 0xbfb8aa3b, v24
	v_exp_f32_e32 v90, v90
	v_exp_f32_e32 v91, v91
	v_pk_add_f32 v[88:89], v[88:89], 1.0 op_sel_hi:[1,0]
	v_div_fmas_f32 v92, v94, v93, v92
	v_div_scale_f32 v95, s[4:5], v89, v89, v27
	v_rcp_f32_e32 v96, v95
	v_div_fixup_f32 v84, v92, v84, v20
	v_pk_add_f32 v[92:93], v[90:91], 1.0 op_sel_hi:[1,0]
	v_fma_f32 v90, -v95, v96, 1.0
	v_fmac_f32_e32 v96, v90, v96
	v_div_scale_f32 v90, vcc, v27, v89, v27
	v_mul_f32_e32 v91, v90, v96
	v_fma_f32 v94, -v95, v91, v90
	v_fmac_f32_e32 v91, v94, v96
	v_div_scale_f32 v94, s[4:5], v88, v88, v26
	v_fma_f32 v90, -v95, v91, v90
	v_rcp_f32_e32 v95, v94
	v_div_fmas_f32 v90, v90, v96, v91
	v_div_fixup_f32 v91, v90, v89, v27
	v_fma_f32 v89, -v94, v95, 1.0
	v_fmac_f32_e32 v95, v89, v95
	v_div_scale_f32 v89, vcc, v26, v88, v26
	v_mul_f32_e32 v90, v89, v95
	v_fma_f32 v96, -v94, v90, v89
	v_fmac_f32_e32 v90, v96, v95
	v_fma_f32 v89, -v94, v90, v89
	v_div_scale_f32 v94, s[4:5], v93, v93, v25
	v_rcp_f32_e32 v96, v94
	v_div_fmas_f32 v89, v89, v95, v90
	v_div_fixup_f32 v90, v89, v88, v26
	v_fma_f32 v88, -v94, v96, 1.0
	v_fmac_f32_e32 v96, v88, v96
	v_div_scale_f32 v88, vcc, v25, v93, v25
	v_mul_f32_e32 v89, v88, v96
	v_fma_f32 v95, -v94, v89, v88
	v_fmac_f32_e32 v89, v95, v96
	v_fma_f32 v88, -v94, v89, v88
	v_div_scale_f32 v94, s[4:5], v92, v92, v24
	v_rcp_f32_e32 v98, v94
	v_div_fmas_f32 v88, v88, v96, v89
	v_div_fixup_f32 v89, v88, v93, v25
	v_mul_f32_e32 v96, 0xbfb8aa3b, v28
	v_fma_f32 v88, -v94, v98, 1.0
	v_fmac_f32_e32 v98, v88, v98
	v_div_scale_f32 v88, vcc, v24, v92, v24
	v_mul_f32_e32 v93, v88, v98
	v_fma_f32 v95, -v94, v93, v88
	v_fmac_f32_e32 v93, v95, v98
	v_fma_f32 v88, -v94, v93, v88
	v_mul_f32_e32 v94, 0xbfb8aa3b, v30
	v_mul_f32_e32 v95, 0xbfb8aa3b, v31
	v_exp_f32_e32 v94, v94
	v_exp_f32_e32 v95, v95
	v_exp_f32_e32 v96, v96
	v_div_fmas_f32 v88, v88, v98, v93
	v_div_fixup_f32 v88, v88, v92, v24
	v_pk_add_f32 v[94:95], v[94:95], 1.0 op_sel_hi:[1,0]
	v_pk_add_f32 v[92:93], v[96:97], 1.0 op_sel_hi:[1,0]
	v_div_scale_f32 v99, s[4:5], v95, v95, v31
	v_rcp_f32_e32 v100, v99
	s_nop 0
	v_fma_f32 v96, -v99, v100, 1.0
	v_fmac_f32_e32 v100, v96, v100
	v_div_scale_f32 v96, vcc, v31, v95, v31
	v_mul_f32_e32 v97, v96, v100
	v_fma_f32 v98, -v99, v97, v96
	v_fmac_f32_e32 v97, v98, v100
	v_div_scale_f32 v98, s[4:5], v94, v94, v30
	v_fma_f32 v96, -v99, v97, v96
	v_rcp_f32_e32 v99, v98
	v_div_fmas_f32 v96, v96, v100, v97
	v_div_fixup_f32 v95, v96, v95, v31
	v_fma_f32 v96, -v98, v99, 1.0
	v_fmac_f32_e32 v99, v96, v99
	v_div_scale_f32 v96, vcc, v30, v94, v30
	v_mul_f32_e32 v97, v96, v99
	v_fma_f32 v100, -v98, v97, v96
	v_fmac_f32_e32 v97, v100, v99
	v_fma_f32 v96, -v98, v97, v96
	v_div_scale_f32 v98, s[4:5], v93, v93, v29
	v_rcp_f32_e32 v100, v98
	v_div_fmas_f32 v96, v96, v99, v97
	v_div_fixup_f32 v94, v96, v94, v30
	v_fma_f32 v96, -v98, v100, 1.0
	v_fmac_f32_e32 v100, v96, v100
	v_div_scale_f32 v96, vcc, v29, v93, v29
	v_mul_f32_e32 v97, v96, v100
	v_fma_f32 v99, -v98, v97, v96
	v_fmac_f32_e32 v97, v99, v100
	v_fma_f32 v96, -v98, v97, v96
	v_div_scale_f32 v98, s[4:5], v92, v92, v28
	v_rcp_f32_e32 v101, v98
	v_div_fmas_f32 v96, v96, v100, v97
	v_div_fixup_f32 v93, v96, v93, v29
	v_mul_f32_e32 v99, 0xbfb8aa3b, v33
	v_fma_f32 v96, -v98, v101, 1.0
	v_fmac_f32_e32 v101, v96, v101
	v_div_scale_f32 v96, vcc, v28, v92, v28
	v_mul_f32_e32 v100, v96, v101
	v_fma_f32 v97, -v98, v100, v96
	v_fmac_f32_e32 v100, v97, v101
	v_fma_f32 v102, -v98, v100, v96
	v_mul_f32_e32 v96, 0xbfb8aa3b, v34
	v_mul_f32_e32 v97, 0xbfb8aa3b, v35
	v_exp_f32_e32 v96, v96
	v_exp_f32_e32 v97, v97
	v_mul_f32_e32 v98, 0xbfb8aa3b, v32
	v_exp_f32_e32 v98, v98
	v_exp_f32_e32 v99, v99
	v_pk_add_f32 v[96:97], v[96:97], 1.0 op_sel_hi:[1,0]
	v_div_fmas_f32 v100, v102, v101, v100
	v_div_scale_f32 v103, s[4:5], v97, v97, v35
	v_rcp_f32_e32 v104, v103
	v_div_fixup_f32 v92, v100, v92, v28
	v_pk_add_f32 v[100:101], v[98:99], 1.0 op_sel_hi:[1,0]
	v_fma_f32 v98, -v103, v104, 1.0
	v_fmac_f32_e32 v104, v98, v104
	v_div_scale_f32 v98, vcc, v35, v97, v35
	v_mul_f32_e32 v99, v98, v104
	v_fma_f32 v102, -v103, v99, v98
	v_fmac_f32_e32 v99, v102, v104
	v_div_scale_f32 v102, s[4:5], v96, v96, v34
	v_fma_f32 v98, -v103, v99, v98
	v_rcp_f32_e32 v103, v102
	v_div_fmas_f32 v98, v98, v104, v99
	v_div_fixup_f32 v99, v98, v97, v35
	v_fma_f32 v97, -v102, v103, 1.0
	v_fmac_f32_e32 v103, v97, v103
	v_div_scale_f32 v97, vcc, v34, v96, v34
	v_mul_f32_e32 v98, v97, v103
	v_fma_f32 v104, -v102, v98, v97
	v_fmac_f32_e32 v98, v104, v103
	v_fma_f32 v97, -v102, v98, v97
	v_div_scale_f32 v102, s[4:5], v101, v101, v33
	v_rcp_f32_e32 v104, v102
	v_div_fmas_f32 v97, v97, v103, v98
	v_div_fixup_f32 v98, v97, v96, v34
	v_fma_f32 v96, -v102, v104, 1.0
	v_fmac_f32_e32 v104, v96, v104
	v_div_scale_f32 v96, vcc, v33, v101, v33
	v_mul_f32_e32 v97, v96, v104
	v_fma_f32 v103, -v102, v97, v96
	v_fmac_f32_e32 v97, v103, v104
	v_fma_f32 v96, -v102, v97, v96
	v_div_scale_f32 v102, s[4:5], v100, v100, v32
	v_rcp_f32_e32 v106, v102
	v_div_fmas_f32 v96, v96, v104, v97
	v_div_fixup_f32 v97, v96, v101, v33
	v_mul_f32_e32 v104, 0xbfb8aa3b, v36
	v_fma_f32 v96, -v102, v106, 1.0
	v_fmac_f32_e32 v106, v96, v106
	v_div_scale_f32 v96, vcc, v32, v100, v32
	v_mul_f32_e32 v101, v96, v106
	v_fma_f32 v103, -v102, v101, v96
	v_fmac_f32_e32 v101, v103, v106
	v_fma_f32 v96, -v102, v101, v96
	v_mul_f32_e32 v102, 0xbfb8aa3b, v38
	v_mul_f32_e32 v103, 0xbfb8aa3b, v39
	v_exp_f32_e32 v102, v102
	v_exp_f32_e32 v103, v103
	v_exp_f32_e32 v104, v104
	v_div_fmas_f32 v96, v96, v106, v101
	v_div_fixup_f32 v96, v96, v100, v32
	v_pk_add_f32 v[102:103], v[102:103], 1.0 op_sel_hi:[1,0]
	v_pk_add_f32 v[100:101], v[104:105], 1.0 op_sel_hi:[1,0]
	v_div_scale_f32 v107, s[4:5], v103, v103, v39
	v_rcp_f32_e32 v108, v107
	s_nop 0
	v_fma_f32 v104, -v107, v108, 1.0
	v_fmac_f32_e32 v108, v104, v108
	v_div_scale_f32 v104, vcc, v39, v103, v39
	v_mul_f32_e32 v105, v104, v108
	v_fma_f32 v106, -v107, v105, v104
	v_fmac_f32_e32 v105, v106, v108
	v_div_scale_f32 v106, s[4:5], v102, v102, v38
	v_fma_f32 v104, -v107, v105, v104
	v_rcp_f32_e32 v107, v106
	v_div_fmas_f32 v104, v104, v108, v105
	v_div_fixup_f32 v103, v104, v103, v39
	v_fma_f32 v104, -v106, v107, 1.0
	v_fmac_f32_e32 v107, v104, v107
	v_div_scale_f32 v104, vcc, v38, v102, v38
	v_mul_f32_e32 v105, v104, v107
	v_fma_f32 v108, -v106, v105, v104
	v_fmac_f32_e32 v105, v108, v107
	v_fma_f32 v104, -v106, v105, v104
	v_div_scale_f32 v106, s[4:5], v101, v101, v37
	v_rcp_f32_e32 v108, v106
	v_div_fmas_f32 v104, v104, v107, v105
	v_div_fixup_f32 v102, v104, v102, v38
	v_fma_f32 v104, -v106, v108, 1.0
	v_fmac_f32_e32 v108, v104, v108
	v_div_scale_f32 v104, vcc, v37, v101, v37
	v_mul_f32_e32 v105, v104, v108
	v_fma_f32 v107, -v106, v105, v104
	v_fmac_f32_e32 v105, v107, v108
	v_fma_f32 v104, -v106, v105, v104
	v_div_scale_f32 v106, s[4:5], v100, v100, v36
	v_rcp_f32_e32 v109, v106
	v_div_fmas_f32 v104, v104, v108, v105
	v_div_fixup_f32 v101, v104, v101, v37
	v_mul_f32_e32 v107, 0xbfb8aa3b, v41
	v_fma_f32 v104, -v106, v109, 1.0
	v_fmac_f32_e32 v109, v104, v109
	v_div_scale_f32 v104, vcc, v36, v100, v36
	v_mul_f32_e32 v108, v104, v109
	v_fma_f32 v105, -v106, v108, v104
	v_fmac_f32_e32 v108, v105, v109
	v_fma_f32 v110, -v106, v108, v104
	v_mul_f32_e32 v104, 0xbfb8aa3b, v42
	v_mul_f32_e32 v105, 0xbfb8aa3b, v43
	v_exp_f32_e32 v104, v104
	v_exp_f32_e32 v105, v105
	v_mul_f32_e32 v106, 0xbfb8aa3b, v40
	v_exp_f32_e32 v106, v106
	v_exp_f32_e32 v107, v107
	v_pk_add_f32 v[104:105], v[104:105], 1.0 op_sel_hi:[1,0]
	v_div_fmas_f32 v108, v110, v109, v108
	v_div_scale_f32 v111, s[4:5], v105, v105, v43
	v_rcp_f32_e32 v112, v111
	v_div_fixup_f32 v100, v108, v100, v36
	v_pk_add_f32 v[108:109], v[106:107], 1.0 op_sel_hi:[1,0]
	v_fma_f32 v106, -v111, v112, 1.0
	v_fmac_f32_e32 v112, v106, v112
	v_div_scale_f32 v106, vcc, v43, v105, v43
	v_mul_f32_e32 v107, v106, v112
	v_fma_f32 v110, -v111, v107, v106
	v_fmac_f32_e32 v107, v110, v112
	v_div_scale_f32 v110, s[4:5], v104, v104, v42
	v_fma_f32 v106, -v111, v107, v106
	v_rcp_f32_e32 v111, v110
	v_div_fmas_f32 v106, v106, v112, v107
	v_div_fixup_f32 v107, v106, v105, v43
	v_fma_f32 v105, -v110, v111, 1.0
	v_fmac_f32_e32 v111, v105, v111
	v_div_scale_f32 v105, vcc, v42, v104, v42
	v_mul_f32_e32 v106, v105, v111
	v_fma_f32 v112, -v110, v106, v105
	v_fmac_f32_e32 v106, v112, v111
	v_fma_f32 v105, -v110, v106, v105
	v_div_scale_f32 v110, s[4:5], v109, v109, v41
	v_rcp_f32_e32 v112, v110
	v_div_fmas_f32 v105, v105, v111, v106
	v_div_fixup_f32 v106, v105, v104, v42
	v_fma_f32 v104, -v110, v112, 1.0
	v_fmac_f32_e32 v112, v104, v112
	v_div_scale_f32 v104, vcc, v41, v109, v41
	v_mul_f32_e32 v105, v104, v112
	v_fma_f32 v111, -v110, v105, v104
	v_fmac_f32_e32 v105, v111, v112
	v_fma_f32 v104, -v110, v105, v104
	v_div_scale_f32 v110, s[4:5], v108, v108, v40
	v_rcp_f32_e32 v114, v110
	v_div_fmas_f32 v104, v104, v112, v105
	v_div_fixup_f32 v105, v104, v109, v41
	v_mul_f32_e32 v112, 0xbfb8aa3b, v44
	v_fma_f32 v104, -v110, v114, 1.0
	v_fmac_f32_e32 v114, v104, v114
	v_div_scale_f32 v104, vcc, v40, v108, v40
	v_mul_f32_e32 v109, v104, v114
	v_fma_f32 v111, -v110, v109, v104
	v_fmac_f32_e32 v109, v111, v114
	v_fma_f32 v104, -v110, v109, v104
	v_mul_f32_e32 v110, 0xbfb8aa3b, v46
	v_mul_f32_e32 v111, 0xbfb8aa3b, v47
	v_exp_f32_e32 v110, v110
	v_exp_f32_e32 v111, v111
	v_exp_f32_e32 v112, v112
	v_div_fmas_f32 v104, v104, v114, v109
	v_div_fixup_f32 v104, v104, v108, v40
	v_pk_add_f32 v[110:111], v[110:111], 1.0 op_sel_hi:[1,0]
	v_pk_add_f32 v[108:109], v[112:113], 1.0 op_sel_hi:[1,0]
	v_div_scale_f32 v115, s[4:5], v111, v111, v47
	v_rcp_f32_e32 v116, v115
	s_nop 0
	v_fma_f32 v112, -v115, v116, 1.0
	v_fmac_f32_e32 v116, v112, v116
	v_div_scale_f32 v112, vcc, v47, v111, v47
	v_mul_f32_e32 v113, v112, v116
	v_fma_f32 v114, -v115, v113, v112
	v_fmac_f32_e32 v113, v114, v116
	v_div_scale_f32 v114, s[4:5], v110, v110, v46
	v_fma_f32 v112, -v115, v113, v112
	v_rcp_f32_e32 v115, v114
	v_div_fmas_f32 v112, v112, v116, v113
	v_div_fixup_f32 v111, v112, v111, v47
	v_fma_f32 v112, -v114, v115, 1.0
	v_fmac_f32_e32 v115, v112, v115
	v_div_scale_f32 v112, vcc, v46, v110, v46
	v_mul_f32_e32 v113, v112, v115
	v_fma_f32 v116, -v114, v113, v112
	v_fmac_f32_e32 v113, v116, v115
	v_fma_f32 v112, -v114, v113, v112
	v_div_scale_f32 v114, s[4:5], v109, v109, v45
	v_rcp_f32_e32 v116, v114
	v_div_fmas_f32 v112, v112, v115, v113
	v_div_fixup_f32 v110, v112, v110, v46
	v_fma_f32 v112, -v114, v116, 1.0
	v_fmac_f32_e32 v116, v112, v116
	v_div_scale_f32 v112, vcc, v45, v109, v45
	v_mul_f32_e32 v113, v112, v116
	v_fma_f32 v115, -v114, v113, v112
	v_fmac_f32_e32 v113, v115, v116
	v_fma_f32 v112, -v114, v113, v112
	v_div_scale_f32 v114, s[4:5], v108, v108, v44
	v_rcp_f32_e32 v117, v114
	v_div_fmas_f32 v112, v112, v116, v113
	v_div_fixup_f32 v109, v112, v109, v45
	v_mul_f32_e32 v115, 0xbfb8aa3b, v49
	v_fma_f32 v112, -v114, v117, 1.0
	v_fmac_f32_e32 v117, v112, v117
	v_div_scale_f32 v112, vcc, v44, v108, v44
	v_mul_f32_e32 v116, v112, v117
	v_fma_f32 v113, -v114, v116, v112
	v_fmac_f32_e32 v116, v113, v117
	v_fma_f32 v118, -v114, v116, v112
	v_mul_f32_e32 v112, 0xbfb8aa3b, v50
	v_mul_f32_e32 v113, 0xbfb8aa3b, v51
	v_exp_f32_e32 v112, v112
	v_exp_f32_e32 v113, v113
	v_mul_f32_e32 v114, 0xbfb8aa3b, v48
	v_exp_f32_e32 v114, v114
	v_exp_f32_e32 v115, v115
	v_pk_add_f32 v[112:113], v[112:113], 1.0 op_sel_hi:[1,0]
	v_div_fmas_f32 v116, v118, v117, v116
	v_div_scale_f32 v119, s[4:5], v113, v113, v51
	v_rcp_f32_e32 v120, v119
	v_div_fixup_f32 v108, v116, v108, v44
	v_pk_add_f32 v[116:117], v[114:115], 1.0 op_sel_hi:[1,0]
	v_fma_f32 v114, -v119, v120, 1.0
	v_fmac_f32_e32 v120, v114, v120
	v_div_scale_f32 v114, vcc, v51, v113, v51
	v_mul_f32_e32 v115, v114, v120
	v_fma_f32 v118, -v119, v115, v114
	v_fmac_f32_e32 v115, v118, v120
	v_div_scale_f32 v118, s[4:5], v112, v112, v50
	v_fma_f32 v114, -v119, v115, v114
	v_rcp_f32_e32 v119, v118
	v_div_fmas_f32 v114, v114, v120, v115
	v_div_fixup_f32 v115, v114, v113, v51
	v_fma_f32 v113, -v118, v119, 1.0
	v_fmac_f32_e32 v119, v113, v119
	v_div_scale_f32 v113, vcc, v50, v112, v50
	v_mul_f32_e32 v114, v113, v119
	v_fma_f32 v120, -v118, v114, v113
	v_fmac_f32_e32 v114, v120, v119
	v_fma_f32 v113, -v118, v114, v113
	v_div_scale_f32 v118, s[4:5], v117, v117, v49
	v_rcp_f32_e32 v120, v118
	v_div_fmas_f32 v113, v113, v119, v114
	v_div_fixup_f32 v114, v113, v112, v50
	v_fma_f32 v112, -v118, v120, 1.0
	v_fmac_f32_e32 v120, v112, v120
	v_div_scale_f32 v112, vcc, v49, v117, v49
	v_mul_f32_e32 v113, v112, v120
	v_fma_f32 v119, -v118, v113, v112
	v_fmac_f32_e32 v113, v119, v120
	v_fma_f32 v112, -v118, v113, v112
	v_div_scale_f32 v118, s[4:5], v116, v116, v48
	v_rcp_f32_e32 v122, v118
	v_div_fmas_f32 v112, v112, v120, v113
	v_div_fixup_f32 v113, v112, v117, v49
	v_mul_f32_e32 v120, 0xbfb8aa3b, v52
	v_fma_f32 v112, -v118, v122, 1.0
	v_fmac_f32_e32 v122, v112, v122
	v_div_scale_f32 v112, vcc, v48, v116, v48
	v_mul_f32_e32 v117, v112, v122
	v_fma_f32 v119, -v118, v117, v112
	v_fmac_f32_e32 v117, v119, v122
	v_fma_f32 v112, -v118, v117, v112
	v_mul_f32_e32 v118, 0xbfb8aa3b, v54
	v_mul_f32_e32 v119, 0xbfb8aa3b, v55
	v_exp_f32_e32 v118, v118
	v_exp_f32_e32 v119, v119
	v_exp_f32_e32 v120, v120
	v_div_fmas_f32 v112, v112, v122, v117
	v_div_fixup_f32 v112, v112, v116, v48
	v_pk_add_f32 v[118:119], v[118:119], 1.0 op_sel_hi:[1,0]
	v_pk_add_f32 v[116:117], v[120:121], 1.0 op_sel_hi:[1,0]
	v_div_scale_f32 v123, s[4:5], v119, v119, v55
	v_rcp_f32_e32 v124, v123
	s_nop 0
	v_fma_f32 v120, -v123, v124, 1.0
	v_fmac_f32_e32 v124, v120, v124
	v_div_scale_f32 v120, vcc, v55, v119, v55
	v_mul_f32_e32 v121, v120, v124
	v_fma_f32 v122, -v123, v121, v120
	v_fmac_f32_e32 v121, v122, v124
	v_div_scale_f32 v122, s[4:5], v118, v118, v54
	v_fma_f32 v120, -v123, v121, v120
	v_rcp_f32_e32 v123, v122
	v_div_fmas_f32 v120, v120, v124, v121
	v_div_fixup_f32 v119, v120, v119, v55
	v_fma_f32 v120, -v122, v123, 1.0
	v_fmac_f32_e32 v123, v120, v123
	v_div_scale_f32 v120, vcc, v54, v118, v54
	v_mul_f32_e32 v121, v120, v123
	v_fma_f32 v124, -v122, v121, v120
	v_fmac_f32_e32 v121, v124, v123
	v_fma_f32 v120, -v122, v121, v120
	v_div_scale_f32 v122, s[4:5], v117, v117, v53
	v_rcp_f32_e32 v124, v122
	v_div_fmas_f32 v120, v120, v123, v121
	v_div_fixup_f32 v118, v120, v118, v54
	v_fma_f32 v120, -v122, v124, 1.0
	v_fmac_f32_e32 v124, v120, v124
	v_div_scale_f32 v120, vcc, v53, v117, v53
	v_mul_f32_e32 v121, v120, v124
	v_fma_f32 v123, -v122, v121, v120
	v_fmac_f32_e32 v121, v123, v124
	v_fma_f32 v120, -v122, v121, v120
	v_div_scale_f32 v122, s[4:5], v116, v116, v52
	v_rcp_f32_e32 v125, v122
	v_div_fmas_f32 v120, v120, v124, v121
	v_div_fixup_f32 v117, v120, v117, v53
	v_mul_f32_e32 v123, 0xbfb8aa3b, v57
	v_fma_f32 v120, -v122, v125, 1.0
	v_fmac_f32_e32 v125, v120, v125
	v_div_scale_f32 v120, vcc, v52, v116, v52
	v_mul_f32_e32 v124, v120, v125
	v_fma_f32 v121, -v122, v124, v120
	v_fmac_f32_e32 v124, v121, v125
	v_fma_f32 v126, -v122, v124, v120
	v_mul_f32_e32 v120, 0xbfb8aa3b, v58
	v_mul_f32_e32 v121, 0xbfb8aa3b, v59
	v_exp_f32_e32 v120, v120
	v_exp_f32_e32 v121, v121
	v_mul_f32_e32 v122, 0xbfb8aa3b, v56
	v_exp_f32_e32 v122, v122
	v_exp_f32_e32 v123, v123
	v_pk_add_f32 v[120:121], v[120:121], 1.0 op_sel_hi:[1,0]
	v_div_fmas_f32 v124, v126, v125, v124
	v_div_scale_f32 v127, s[4:5], v121, v121, v59
	v_rcp_f32_e32 v142, v127
	v_div_fixup_f32 v116, v124, v116, v52
	v_pk_add_f32 v[124:125], v[122:123], 1.0 op_sel_hi:[1,0]
	v_fma_f32 v122, -v127, v142, 1.0
	v_fmac_f32_e32 v142, v122, v142
	v_div_scale_f32 v122, vcc, v59, v121, v59
	v_mul_f32_e32 v123, v122, v142
	v_fma_f32 v126, -v127, v123, v122
	v_fmac_f32_e32 v123, v126, v142
	v_div_scale_f32 v126, s[4:5], v120, v120, v58
	v_fma_f32 v122, -v127, v123, v122
	v_rcp_f32_e32 v127, v126
	v_div_fmas_f32 v122, v122, v142, v123
	v_div_fixup_f32 v123, v122, v121, v59
	v_fma_f32 v121, -v126, v127, 1.0
	v_fmac_f32_e32 v127, v121, v127
	v_div_scale_f32 v121, vcc, v58, v120, v58
	v_mul_f32_e32 v122, v121, v127
	v_fma_f32 v142, -v126, v122, v121
	v_fmac_f32_e32 v122, v142, v127
	v_fma_f32 v121, -v126, v122, v121
	v_div_scale_f32 v126, s[4:5], v125, v125, v57
	v_rcp_f32_e32 v142, v126
	v_div_fmas_f32 v121, v121, v127, v122
	v_div_fixup_f32 v122, v121, v120, v58
	v_fma_f32 v120, -v126, v142, 1.0
	v_fmac_f32_e32 v142, v120, v142
	v_div_scale_f32 v120, vcc, v57, v125, v57
	v_mul_f32_e32 v121, v120, v142
	v_fma_f32 v127, -v126, v121, v120
	v_fmac_f32_e32 v121, v127, v142
	v_fma_f32 v120, -v126, v121, v120
	v_div_scale_f32 v126, s[4:5], v124, v124, v56
	v_rcp_f32_e32 v202, v126
	v_div_fmas_f32 v120, v120, v142, v121
	v_div_fixup_f32 v121, v120, v125, v57
	v_mul_f32_e32 v142, 0xbfb8aa3b, v60
	v_fma_f32 v120, -v126, v202, 1.0
	v_fmac_f32_e32 v202, v120, v202
	v_div_scale_f32 v120, vcc, v56, v124, v56
	v_mul_f32_e32 v125, v120, v202
	v_fma_f32 v127, -v126, v125, v120
	v_fmac_f32_e32 v125, v127, v202
	v_fma_f32 v120, -v126, v125, v120
	v_mul_f32_e32 v126, 0xbfb8aa3b, v62
	v_mul_f32_e32 v127, 0xbfb8aa3b, v63
	v_exp_f32_e32 v126, v126
	v_exp_f32_e32 v127, v127
	v_exp_f32_e32 v200, v142
	v_mul_f32_e32 v142, 0xbfb8aa3b, v61
	v_exp_f32_e32 v201, v142
	v_pk_add_f32 v[126:127], v[126:127], 1.0 op_sel_hi:[1,0]
	v_div_fmas_f32 v120, v120, v202, v125
	v_div_scale_f32 v142, s[4:5], v127, v127, v63
	v_rcp_f32_e32 v203, v142
	v_div_fixup_f32 v120, v120, v124, v56
	v_pk_add_f32 v[124:125], v[200:201], 1.0 op_sel_hi:[1,0]
	v_fma_f32 v200, -v142, v203, 1.0
	v_fmac_f32_e32 v203, v200, v203
	v_div_scale_f32 v200, vcc, v63, v127, v63
	v_mul_f32_e32 v201, v200, v203
	v_fma_f32 v202, -v142, v201, v200
	v_fmac_f32_e32 v201, v202, v203
	v_fma_f32 v142, -v142, v201, v200
	v_div_scale_f32 v200, s[4:5], v126, v126, v62
	v_rcp_f32_e32 v202, v200
	v_div_fmas_f32 v142, v142, v203, v201
	v_div_fixup_f32 v127, v142, v127, v63
	v_fma_f32 v142, -v200, v202, 1.0
	v_fmac_f32_e32 v202, v142, v202
	v_div_scale_f32 v142, vcc, v62, v126, v62
	v_mul_f32_e32 v201, v142, v202
	v_fma_f32 v203, -v200, v201, v142
	v_fmac_f32_e32 v201, v203, v202
	v_fma_f32 v142, -v200, v201, v142
	v_div_scale_f32 v200, s[4:5], v125, v125, v61
	v_rcp_f32_e32 v203, v200
	v_div_fmas_f32 v142, v142, v202, v201
	v_div_fixup_f32 v126, v142, v126, v62
	v_fma_f32 v142, -v200, v203, 1.0
	v_fmac_f32_e32 v203, v142, v203
	v_div_scale_f32 v142, vcc, v61, v125, v61
	v_mul_f32_e32 v201, v142, v203
	v_fma_f32 v202, -v200, v201, v142
	v_fmac_f32_e32 v201, v202, v203
	v_fma_f32 v142, -v200, v201, v142
	v_div_scale_f32 v200, s[4:5], v124, v124, v60
	v_rcp_f32_e32 v202, v200
	v_div_fmas_f32 v142, v142, v203, v201
	v_div_fixup_f32 v125, v142, v125, v61
	s_lshl_b64 s[4:5], s[66:67], 19
	v_fma_f32 v142, -v200, v202, 1.0
	v_fmac_f32_e32 v202, v142, v202
	v_div_scale_f32 v142, vcc, v60, v124, v60
	s_add_u32 s4, s36, s4
	v_mul_f32_e32 v201, v142, v202
	s_addc_u32 s5, s37, s5
	s_lshl_b32 s34, s0, 7
	v_fma_f32 v203, -v200, v201, v142
	s_lshl_b64 s[0:1], s[34:35], 1
	v_fmac_f32_e32 v201, v203, v202
	s_add_u32 s0, s4, s0
	v_fma_f32 v142, -v200, v201, v142
	s_addc_u32 s1, s5, s1
	v_div_fmas_f32 v142, v142, v202, v201
	s_add_u32 s4, s0, 0xffffd800
	v_div_fixup_f32 v124, v142, v124, v60
	s_addc_u32 s5, s1, -1
